# passC2 norm-weight loads hoisted, weight-transpose loads de-serialized and rebalanced across waves, VMT GEMM on other blocks
# speedup vs baseline: 1.0133x; 1.0133x over previous
.LBB0_549:
	s_or_b64 exec, exec, s[0:1]
	s_mov_b64 s[0:1], 0
	v_mov_b32_e32 v2, v190
	s_waitcnt lgkmcnt(0)
	s_barrier
	v_readlane_b32 s21, v253, 55
	v_and_b32_e32 v82, 15, v2
	v_ashrrev_i32_e32 v2, 2, v2
	v_and_b32_e32 v72, -4, v2
	v_lshl_add_u64 v[0:1], v[200:201], 0, s[0:1]
	v_ashrrev_i32_e32 v73, 31, v72
	v_lshl_add_u64 v[68:69], v[72:73], 2, v[0:1]
	v_lshl_add_u32 v0, v82, 2, s21
	v_or_b32_e32 v70, s58, v82
	v_mov_b32_e32 v71, s59
	ds_read2st64_b32 v[78:79], v0 offset1:1
	ds_read2st64_b32 v[84:85], v0 offset0:2 offset1:3
	ds_read2st64_b32 v[86:87], v0 offset0:4 offset1:5
	ds_read2st64_b32 v[88:89], v0 offset0:6 offset1:7
	v_lshlrev_b64 v[0:1], 11, v[70:71]
	v_lshl_add_u64 v[0:1], s[54:55], 0, v[0:1]
	v_lshl_add_u64 v[74:75], v[0:1], 0, v[192:193]
	global_load_dwordx4 v[0:3], v[68:69], off
	global_load_dwordx4 v[100:103], v[68:69], off
	global_load_dwordx4 v[104:107], v[68:69], off offset:64
	global_load_dwordx4 v[108:111], v[68:69], off offset:128
	global_load_dwordx4 v[112:115], v[68:69], off offset:192
	v_or_b32_e32 v83, 16, v82
	v_lshl_add_u32 v70, v83, 2, s21
	s_waitcnt lgkmcnt(3)
	v_mov_b32_e32 v97, v78
	s_mov_b32 s0, 0x3727c5ac
	s_mov_b32 s34, 0x3b000000
	s_mov_b32 s20, 0x800000
	s_mov_b32 s22, 0x20600000
	s_mov_b64 s[26:27], 0x20600200
	s_add_i32 s2, s2, s3
	v_lshl_add_u64 v[206:207], v[206:207], 0, s[56:57]
	v_mov_b32_e32 v230, v170
	s_waitcnt vmcnt(0)
	v_mov_b32_e32 v80, v0
	v_mov_b32_e32 v81, v2
	v_mov_b32_e32 v2, v1
	v_lshlrev_b64 v[0:1], 1, v[72:73]
	ds_read2st64_b32 v[72:73], v70 offset1:1
	ds_read2st64_b32 v[90:91], v70 offset0:2 offset1:3
	ds_read2st64_b32 v[92:93], v70 offset0:4 offset1:5
	ds_read2st64_b32 v[94:95], v70 offset0:6 offset1:7
	v_lshl_add_u64 v[76:77], v[74:75], 0, v[0:1]
	s_waitcnt lgkmcnt(3)
	v_mov_b32_e32 v96, v72
	v_pk_add_f32 v[96:97], v[96:97], 0 op_sel_hi:[1,0]
	v_mov_b32_e32 v78, v73
	v_pk_add_f32 v[72:73], v[96:97], v[78:79]
	s_waitcnt lgkmcnt(2)
	v_mov_b32_e32 v78, v90
	v_mov_b32_e32 v79, v84
	v_pk_add_f32 v[72:73], v[72:73], v[78:79]
	v_mov_b32_e32 v84, v91
	v_pk_add_f32 v[72:73], v[72:73], v[84:85]
	s_waitcnt lgkmcnt(1)
	v_mov_b32_e32 v78, v92
	v_mov_b32_e32 v79, v86
	v_pk_add_f32 v[72:73], v[72:73], v[78:79]
	v_mov_b32_e32 v86, v93
	v_pk_add_f32 v[72:73], v[72:73], v[86:87]
	s_waitcnt lgkmcnt(0)
	v_mov_b32_e32 v78, v94
	v_mov_b32_e32 v79, v88
	v_pk_add_f32 v[72:73], v[72:73], v[78:79]
	v_mov_b32_e32 v88, v95
	v_pk_add_f32 v[78:79], v[72:73], v[88:89]
	v_mov_b64_e32 v[72:73], s[0:1]
	v_pk_fma_f32 v[78:79], v[78:79], s[34:35], v[72:73] op_sel_hi:[1,0,0]
	v_lshl_add_u64 v[74:75], v[76:77], 0, s[26:27]
	v_mul_f32_e32 v70, 0x4b800000, v79
	v_cmp_gt_f32_e64 s[0:1], s20, v79
	v_cmp_gt_f32_e32 vcc, s20, v78
	s_nop 0
	v_cndmask_b32_e64 v70, v79, v70, s[0:1]
	v_rsq_f32_e32 v70, v70
	s_nop 0
	v_mul_f32_e32 v79, 0x45800000, v70
	v_cndmask_b32_e64 v70, v70, v79, s[0:1]
	v_pk_mul_f32 v[54:55], v[54:55], v[70:71] op_sel_hi:[1,0]
	v_pk_mul_f32 v[58:59], v[58:59], v[70:71] op_sel_hi:[1,0]
	v_pk_mul_f32 v[54:55], v[80:81], v[54:55]
	v_pk_mul_f32 v[2:3], v[2:3], v[58:59]
	v_cvt_pk_bf16_f32 v2, v54, v2
	v_add_co_u32_e64 v54, s[0:1], s22, v76
	v_cvt_pk_bf16_f32 v3, v55, v3
	s_nop 0
	v_addc_co_u32_e64 v55, s[0:1], 0, v77, s[0:1]
	global_store_dwordx2 v[54:55], v[2:3], off offset:512
	v_mov_b32_e32 v84, v104
	v_mov_b32_e32 v85, v105
	v_mov_b32_e32 v86, v106
	v_mov_b32_e32 v87, v107
	v_pk_mul_f32 v[2:3], v[56:57], v[70:71] op_sel_hi:[1,0]
	v_pk_mul_f32 v[52:53], v[52:53], v[70:71] op_sel_hi:[1,0]
	v_pk_mul_f32 v[50:51], v[50:51], v[70:71] op_sel_hi:[1,0]
	v_mov_b32_e32 v54, v84
	v_mov_b32_e32 v55, v86
	v_pk_mul_f32 v[2:3], v[54:55], v[2:3]
	v_mov_b32_e32 v86, v85
	v_pk_mul_f32 v[52:53], v[86:87], v[52:53]
	v_cvt_pk_bf16_f32 v3, v3, v53
	v_cvt_pk_bf16_f32 v2, v2, v52
	global_store_dwordx2 v[74:75], v[2:3], off offset:32
	v_mov_b32_e32 v52, v108
	v_mov_b32_e32 v53, v109
	v_mov_b32_e32 v54, v110
	v_mov_b32_e32 v55, v111
	v_pk_mul_f32 v[2:3], v[64:65], v[70:71] op_sel_hi:[1,0]
	v_mov_b32_e32 v56, v52
	v_mov_b32_e32 v57, v54
	v_pk_mul_f32 v[2:3], v[56:57], v[2:3]
	v_pk_mul_f32 v[56:57], v[60:61], v[70:71] op_sel_hi:[1,0]
	v_mov_b32_e32 v54, v53
	v_pk_mul_f32 v[52:53], v[54:55], v[56:57]
	v_cvt_pk_bf16_f32 v3, v3, v53
	v_cvt_pk_bf16_f32 v2, v2, v52
	global_store_dwordx2 v[74:75], v[2:3], off offset:64
	v_mov_b32_e32 v52, v112
	v_mov_b32_e32 v53, v113
	v_mov_b32_e32 v54, v114
	v_mov_b32_e32 v55, v115
	v_pk_mul_f32 v[2:3], v[62:63], v[70:71] op_sel_hi:[1,0]
	v_or_b32_e32 v70, s58, v83
	v_mov_b32_e32 v56, v52
	v_mov_b32_e32 v57, v54
	v_pk_mul_f32 v[2:3], v[56:57], v[2:3]
	v_mov_b32_e32 v54, v53
	v_pk_mul_f32 v[50:51], v[54:55], v[50:51]
	v_cvt_pk_bf16_f32 v3, v3, v51
	v_cvt_pk_bf16_f32 v2, v2, v50
	v_lshlrev_b64 v[50:51], 11, v[70:71]
	global_store_dwordx2 v[74:75], v[2:3], off offset:96
	v_lshl_add_u64 v[50:51], s[54:55], 0, v[50:51]
	v_lshl_add_u64 v[54:55], v[50:51], 0, v[192:193]
	v_mov_b32_e32 v50, v100
	v_mov_b32_e32 v51, v101
	v_mov_b32_e32 v52, v102
	v_mov_b32_e32 v53, v103
	v_mul_f32_e32 v2, 0x4b800000, v78
	v_cndmask_b32_e32 v2, v78, v2, vcc
	v_rsq_f32_e32 v2, v2
	v_mov_b32_e32 v56, v50
	v_mul_f32_e32 v3, 0x45800000, v2
	v_cndmask_b32_e32 v2, v2, v3, vcc
	v_pk_mul_f32 v[48:49], v[48:49], v[2:3] op_sel_hi:[1,0]
	v_mov_b32_e32 v57, v52
	v_pk_mul_f32 v[48:49], v[56:57], v[48:49]
	v_pk_mul_f32 v[46:47], v[46:47], v[2:3] op_sel_hi:[1,0]
	v_mov_b32_e32 v52, v51
	v_pk_mul_f32 v[46:47], v[52:53], v[46:47]
	v_and_b32_sdwa v3, v49, v228 dst_sel:DWORD dst_unused:UNUSED_PAD src0_sel:WORD_1 src1_sel:DWORD
	s_nop 0
	v_add3_u32 v3, v49, v3, s96
	v_and_b32_sdwa v49, v47, v228 dst_sel:DWORD dst_unused:UNUSED_PAD src0_sel:WORD_1 src1_sel:DWORD
	s_nop 0
	v_add3_u32 v47, v47, v49, s96
	v_and_b32_e32 v47, 0xffff0000, v47
	v_lshl_add_u64 v[50:51], v[54:55], 0, v[0:1]
	v_or_b32_sdwa v49, v47, v3 dst_sel:DWORD dst_unused:UNUSED_PAD src0_sel:DWORD src1_sel:WORD_1
	v_cvt_pk_bf16_f32 v48, v48, v46
	v_lshl_add_u64 v[46:47], v[50:51], 0, s[26:27]
	v_add_co_u32_e32 v50, vcc, s22, v50
	v_pk_mul_f32 v[44:45], v[44:45], v[2:3] op_sel_hi:[1,0]
	s_nop 0
	v_addc_co_u32_e32 v51, vcc, 0, v51, vcc
	global_store_dwordx2 v[50:51], v[48:49], off offset:512
	v_mov_b32_e32 v48, v104
	v_mov_b32_e32 v49, v105
	v_mov_b32_e32 v50, v106
	v_mov_b32_e32 v51, v107
	v_pk_mul_f32 v[40:41], v[40:41], v[2:3] op_sel_hi:[1,0]
	v_mov_b32_e32 v52, v48
	v_mov_b32_e32 v53, v50
	v_pk_mul_f32 v[44:45], v[52:53], v[44:45]
	v_mov_b32_e32 v50, v49
	v_pk_mul_f32 v[40:41], v[50:51], v[40:41]
	v_and_b32_sdwa v3, v45, v228 dst_sel:DWORD dst_unused:UNUSED_PAD src0_sel:WORD_1 src1_sel:DWORD
	s_nop 0
	v_add3_u32 v3, v45, v3, s96
	v_and_b32_sdwa v45, v41, v228 dst_sel:DWORD dst_unused:UNUSED_PAD src0_sel:WORD_1 src1_sel:DWORD
	s_nop 0
	v_add3_u32 v41, v41, v45, s96
	v_and_b32_e32 v41, 0xffff0000, v41
	v_or_b32_sdwa v41, v41, v3 dst_sel:DWORD dst_unused:UNUSED_PAD src0_sel:DWORD src1_sel:WORD_1
	v_cvt_pk_bf16_f32 v40, v44, v40
	global_store_dwordx2 v[46:47], v[40:41], off offset:32
	v_mov_b32_e32 v48, v108
	v_mov_b32_e32 v49, v109
	v_mov_b32_e32 v50, v110
	v_mov_b32_e32 v51, v111
	v_pk_mul_f32 v[40:41], v[42:43], v[2:3] op_sel_hi:[1,0]
	v_pk_mul_f32 v[36:37], v[36:37], v[2:3] op_sel_hi:[1,0]
	v_mov_b32_e32 v42, v48
	v_mov_b32_e32 v43, v50
	v_pk_mul_f32 v[40:41], v[42:43], v[40:41]
	v_mov_b32_e32 v50, v49
	v_pk_mul_f32 v[36:37], v[50:51], v[36:37]
	v_and_b32_sdwa v3, v41, v228 dst_sel:DWORD dst_unused:UNUSED_PAD src0_sel:WORD_1 src1_sel:DWORD
	s_nop 0
	v_add3_u32 v3, v41, v3, s96
	v_and_b32_sdwa v41, v37, v228 dst_sel:DWORD dst_unused:UNUSED_PAD src0_sel:WORD_1 src1_sel:DWORD
	s_nop 0
	v_add3_u32 v37, v37, v41, s96
	v_and_b32_e32 v37, 0xffff0000, v37
	v_or_b32_sdwa v37, v37, v3 dst_sel:DWORD dst_unused:UNUSED_PAD src0_sel:DWORD src1_sel:WORD_1
	v_cvt_pk_bf16_f32 v36, v40, v36
	global_store_dwordx2 v[46:47], v[36:37], off offset:64
	v_mov_b32_e32 v40, v112
	v_mov_b32_e32 v41, v113
	v_mov_b32_e32 v42, v114
	v_mov_b32_e32 v43, v115
	v_pk_mul_f32 v[36:37], v[38:39], v[2:3] op_sel_hi:[1,0]
	v_pk_mul_f32 v[2:3], v[34:35], v[2:3] op_sel_hi:[1,0]
	v_mov_b32_e32 v38, v40
	v_mov_b32_e32 v39, v42
	v_pk_mul_f32 v[36:37], v[38:39], v[36:37]
	v_mov_b32_e32 v42, v41
	v_pk_mul_f32 v[2:3], v[42:43], v[2:3]
	v_and_b32_sdwa v34, v37, v228 dst_sel:DWORD dst_unused:UNUSED_PAD src0_sel:WORD_1 src1_sel:DWORD
	v_and_b32_sdwa v35, v36, v228 dst_sel:DWORD dst_unused:UNUSED_PAD src0_sel:WORD_1 src1_sel:DWORD
	v_add3_u32 v35, v36, v35, s96
	v_add3_u32 v34, v37, v34, s96
	v_and_b32_sdwa v36, v3, v228 dst_sel:DWORD dst_unused:UNUSED_PAD src0_sel:WORD_1 src1_sel:DWORD
	v_and_b32_sdwa v37, v2, v228 dst_sel:DWORD dst_unused:UNUSED_PAD src0_sel:WORD_1 src1_sel:DWORD
	v_add3_u32 v3, v3, v36, s96
	v_add3_u32 v2, v2, v37, s96
	v_and_b32_e32 v3, 0xffff0000, v3
	v_and_b32_e32 v2, 0xffff0000, v2
	v_or_b32_sdwa v3, v3, v34 dst_sel:DWORD dst_unused:UNUSED_PAD src0_sel:DWORD src1_sel:WORD_1
	v_or_b32_sdwa v2, v2, v35 dst_sel:DWORD dst_unused:UNUSED_PAD src0_sel:DWORD src1_sel:WORD_1
	global_store_dwordx2 v[46:47], v[2:3], off offset:96
	v_or_b32_e32 v2, 32, v82
	v_lshl_add_u32 v3, v2, 2, s21
	ds_read2st64_b32 v[34:35], v3 offset1:1
	ds_read2st64_b32 v[42:43], v3 offset0:2 offset1:3
	ds_read2st64_b32 v[44:45], v3 offset0:4 offset1:5
	ds_read2st64_b32 v[46:47], v3 offset0:6 offset1:7
	v_mov_b32_e32 v38, v100
	v_mov_b32_e32 v39, v101
	v_mov_b32_e32 v40, v102
	v_mov_b32_e32 v41, v103
	v_or_b32_e32 v37, 48, v82
	v_lshl_add_u32 v36, v37, 2, s21
	ds_read2st64_b32 v[50:51], v36 offset1:1
	ds_read2st64_b32 v[52:53], v36 offset0:2 offset1:3
	ds_read2st64_b32 v[54:55], v36 offset0:4 offset1:5
	ds_read2st64_b32 v[56:57], v36 offset0:6 offset1:7
	s_waitcnt lgkmcnt(7)
	v_mov_b32_e32 v59, v34
	s_waitcnt lgkmcnt(3)
	v_mov_b32_e32 v58, v50
	v_pk_add_f32 v[58:59], v[58:59], 0 op_sel_hi:[1,0]
	v_mov_b32_e32 v34, v51
	v_pk_add_f32 v[34:35], v[58:59], v[34:35]
	s_waitcnt lgkmcnt(2)
	v_mov_b32_e32 v50, v52
	v_mov_b32_e32 v51, v42
	v_pk_add_f32 v[34:35], v[34:35], v[50:51]
	v_mov_b32_e32 v42, v53
	v_pk_add_f32 v[34:35], v[34:35], v[42:43]
	s_waitcnt lgkmcnt(1)
	v_mov_b32_e32 v42, v54
	v_mov_b32_e32 v43, v44
	v_pk_add_f32 v[34:35], v[34:35], v[42:43]
	v_mov_b32_e32 v44, v55
	v_pk_add_f32 v[34:35], v[34:35], v[44:45]
	s_waitcnt lgkmcnt(0)
	v_mov_b32_e32 v42, v56
	v_mov_b32_e32 v43, v46
	v_pk_add_f32 v[34:35], v[34:35], v[42:43]
	v_mov_b32_e32 v46, v57
	v_pk_add_f32 v[34:35], v[34:35], v[46:47]
	v_or_b32_e32 v70, s58, v2
	v_pk_fma_f32 v[34:35], v[34:35], s[34:35], v[72:73] op_sel_hi:[1,0,0]
	v_lshlrev_b64 v[2:3], 11, v[70:71]
	v_mul_f32_e32 v36, 0x4b800000, v35
	v_cmp_gt_f32_e64 s[0:1], s20, v35
	v_lshl_add_u64 v[2:3], s[54:55], 0, v[2:3]
	v_lshl_add_u64 v[2:3], v[2:3], 0, v[192:193]
	v_cndmask_b32_e64 v35, v35, v36, s[0:1]
	v_rsq_f32_e32 v35, v35
	v_or_b32_e32 v70, s58, v37
	v_cmp_gt_f32_e32 vcc, s20, v34
	v_mul_f32_e32 v36, 0x45800000, v35
	v_cndmask_b32_e64 v36, v35, v36, s[0:1]
	v_pk_mul_f32 v[32:33], v[32:33], v[36:37] op_sel_hi:[1,0]
	v_pk_mul_f32 v[30:31], v[30:31], v[36:37] op_sel_hi:[1,0]
	v_pk_mul_f32 v[28:29], v[28:29], v[36:37] op_sel_hi:[1,0]
	v_pk_mul_f32 v[24:25], v[24:25], v[36:37] op_sel_hi:[1,0]
	v_pk_mul_f32 v[20:21], v[20:21], v[36:37] op_sel_hi:[1,0]
	v_pk_mul_f32 v[18:19], v[18:19], v[36:37] op_sel_hi:[1,0]
	v_mov_b32_e32 v48, v38
	v_mov_b32_e32 v49, v40
	v_mov_b32_e32 v40, v39
	v_pk_mul_f32 v[32:33], v[48:49], v[32:33]
	v_pk_mul_f32 v[30:31], v[40:41], v[30:31]
	v_lshl_add_u64 v[38:39], v[2:3], 0, v[0:1]
	v_cvt_pk_bf16_f32 v30, v32, v30
	v_add_co_u32_e64 v32, s[0:1], s22, v38
	v_cvt_pk_bf16_f32 v31, v33, v31
	s_nop 0
	v_addc_co_u32_e64 v33, s[0:1], 0, v39, s[0:1]
	global_store_dwordx2 v[32:33], v[30:31], off offset:512
	v_mov_b32_e32 v30, v104
	v_mov_b32_e32 v31, v105
	v_mov_b32_e32 v32, v106
	v_mov_b32_e32 v33, v107
	v_lshl_add_u64 v[2:3], v[38:39], 0, s[26:27]
	v_readlane_b32 s0, v254, 19
	s_add_i32 s24, s24, s0
	s_cmpk_lt_i32 s24, 0x400
	v_readlane_b32 s1, v254, 20
	v_mov_b32_e32 v38, v30
	v_mov_b32_e32 v39, v32
	v_pk_mul_f32 v[28:29], v[38:39], v[28:29]
	v_mov_b32_e32 v32, v31
	v_pk_mul_f32 v[24:25], v[32:33], v[24:25]
	v_cvt_pk_bf16_f32 v25, v29, v25
	v_cvt_pk_bf16_f32 v24, v28, v24
	global_store_dwordx2 v[2:3], v[24:25], off offset:32
	v_mov_b32_e32 v28, v108
	v_mov_b32_e32 v29, v109
	v_mov_b32_e32 v30, v110
	v_mov_b32_e32 v31, v111
	v_pk_mul_f32 v[24:25], v[26:27], v[36:37] op_sel_hi:[1,0]
	v_mov_b32_e32 v26, v28
	v_mov_b32_e32 v27, v30
	v_pk_mul_f32 v[24:25], v[26:27], v[24:25]
	v_mov_b32_e32 v30, v29
	v_pk_mul_f32 v[20:21], v[30:31], v[20:21]
	v_cvt_pk_bf16_f32 v21, v25, v21
	v_cvt_pk_bf16_f32 v20, v24, v20
	global_store_dwordx2 v[2:3], v[20:21], off offset:64
	v_mov_b32_e32 v24, v112
	v_mov_b32_e32 v25, v113
	v_mov_b32_e32 v26, v114
	v_mov_b32_e32 v27, v115
	v_pk_mul_f32 v[20:21], v[22:23], v[36:37] op_sel_hi:[1,0]
	v_mov_b32_e32 v22, v24
	v_mov_b32_e32 v23, v26
	v_pk_mul_f32 v[20:21], v[22:23], v[20:21]
	v_mov_b32_e32 v26, v25
	v_pk_mul_f32 v[18:19], v[26:27], v[18:19]
	v_cvt_pk_bf16_f32 v19, v21, v19
	v_cvt_pk_bf16_f32 v18, v20, v18
	global_store_dwordx2 v[2:3], v[18:19], off offset:96
	v_lshlrev_b64 v[18:19], 11, v[70:71]
	v_lshl_add_u64 v[18:19], s[54:55], 0, v[18:19]
	v_lshl_add_u64 v[22:23], v[18:19], 0, v[192:193]
	v_mov_b32_e32 v18, v100
	v_mov_b32_e32 v19, v101
	v_mov_b32_e32 v20, v102
	v_mov_b32_e32 v21, v103
	v_mul_f32_e32 v2, 0x4b800000, v34
	v_cndmask_b32_e32 v2, v34, v2, vcc
	v_rsq_f32_e32 v2, v2
	v_mov_b32_e32 v24, v18
	v_mul_f32_e32 v3, 0x45800000, v2
	v_cndmask_b32_e32 v2, v2, v3, vcc
	v_pk_mul_f32 v[16:17], v[16:17], v[2:3] op_sel_hi:[1,0]
	v_mov_b32_e32 v25, v20
	v_pk_mul_f32 v[16:17], v[24:25], v[16:17]
	v_pk_mul_f32 v[14:15], v[14:15], v[2:3] op_sel_hi:[1,0]
	v_mov_b32_e32 v20, v19
	v_pk_mul_f32 v[14:15], v[20:21], v[14:15]
	v_and_b32_sdwa v3, v17, v228 dst_sel:DWORD dst_unused:UNUSED_PAD src0_sel:WORD_1 src1_sel:DWORD
	s_nop 0
	v_add3_u32 v3, v17, v3, s96
	v_and_b32_sdwa v17, v15, v228 dst_sel:DWORD dst_unused:UNUSED_PAD src0_sel:WORD_1 src1_sel:DWORD
	s_nop 0
	v_add3_u32 v15, v15, v17, s96
	v_cvt_pk_bf16_f32 v14, v16, v14
	v_lshl_add_u64 v[16:17], v[22:23], 0, v[0:1]
	v_and_b32_e32 v15, 0xffff0000, v15
	v_lshl_add_u64 v[0:1], v[16:17], 0, s[26:27]
	v_add_co_u32_e32 v16, vcc, s22, v16
	v_or_b32_sdwa v15, v15, v3 dst_sel:DWORD dst_unused:UNUSED_PAD src0_sel:DWORD src1_sel:WORD_1
	s_nop 0
	v_addc_co_u32_e32 v17, vcc, 0, v17, vcc
	global_store_dwordx2 v[16:17], v[14:15], off offset:512
	v_mov_b32_e32 v14, v104
	v_mov_b32_e32 v15, v105
	v_mov_b32_e32 v16, v106
	v_mov_b32_e32 v17, v107
	v_pk_mul_f32 v[12:13], v[12:13], v[2:3] op_sel_hi:[1,0]
	v_pk_mul_f32 v[8:9], v[8:9], v[2:3] op_sel_hi:[1,0]
	v_mov_b32_e32 v18, v14
	v_mov_b32_e32 v19, v16
	v_pk_mul_f32 v[12:13], v[18:19], v[12:13]
	v_mov_b32_e32 v16, v15
	v_pk_mul_f32 v[8:9], v[16:17], v[8:9]
	v_and_b32_sdwa v3, v13, v228 dst_sel:DWORD dst_unused:UNUSED_PAD src0_sel:WORD_1 src1_sel:DWORD
	s_nop 0
	v_add3_u32 v3, v13, v3, s96
	v_and_b32_sdwa v13, v9, v228 dst_sel:DWORD dst_unused:UNUSED_PAD src0_sel:WORD_1 src1_sel:DWORD
	s_nop 0
	v_add3_u32 v9, v9, v13, s96
	v_and_b32_e32 v9, 0xffff0000, v9
	v_or_b32_sdwa v9, v9, v3 dst_sel:DWORD dst_unused:UNUSED_PAD src0_sel:DWORD src1_sel:WORD_1
	v_cvt_pk_bf16_f32 v8, v12, v8
	global_store_dwordx2 v[0:1], v[8:9], off offset:32
	v_mov_b32_e32 v12, v108
	v_mov_b32_e32 v13, v109
	v_mov_b32_e32 v14, v110
	v_mov_b32_e32 v15, v111
	v_pk_mul_f32 v[8:9], v[10:11], v[2:3] op_sel_hi:[1,0]
	v_pk_mul_f32 v[4:5], v[4:5], v[2:3] op_sel_hi:[1,0]
	v_mov_b32_e32 v10, v12
	v_mov_b32_e32 v11, v14
	v_pk_mul_f32 v[8:9], v[10:11], v[8:9]
	v_mov_b32_e32 v14, v13
	v_pk_mul_f32 v[4:5], v[14:15], v[4:5]
	v_and_b32_sdwa v3, v9, v228 dst_sel:DWORD dst_unused:UNUSED_PAD src0_sel:WORD_1 src1_sel:DWORD
	s_nop 0
	v_add3_u32 v3, v9, v3, s96
	v_and_b32_sdwa v9, v5, v228 dst_sel:DWORD dst_unused:UNUSED_PAD src0_sel:WORD_1 src1_sel:DWORD
	s_nop 0
	v_add3_u32 v5, v5, v9, s96
	v_and_b32_e32 v5, 0xffff0000, v5
	v_or_b32_sdwa v5, v5, v3 dst_sel:DWORD dst_unused:UNUSED_PAD src0_sel:DWORD src1_sel:WORD_1
	v_cvt_pk_bf16_f32 v4, v8, v4
	global_store_dwordx2 v[0:1], v[4:5], off offset:64
	v_mov_b32_e32 v8, v112
	v_mov_b32_e32 v9, v113
	v_mov_b32_e32 v10, v114
	v_mov_b32_e32 v11, v115
	v_pk_mul_f32 v[4:5], v[6:7], v[2:3] op_sel_hi:[1,0]
	v_pk_mul_f32 v[2:3], v[66:67], v[2:3] op_sel_hi:[1,0]
	v_mov_b32_e32 v6, v8
	v_mov_b32_e32 v7, v10
	v_pk_mul_f32 v[4:5], v[6:7], v[4:5]
	v_mov_b32_e32 v10, v9
	v_pk_mul_f32 v[2:3], v[10:11], v[2:3]
	v_cvt_pk_bf16_f32 v3, v5, v3
	v_cvt_pk_bf16_f32 v2, v4, v2
	global_store_dwordx2 v[0:1], v[2:3], off offset:96
	s_barrier
	s_cbranch_scc0 .LBB0_556

.LBB0_956:
	s_add_i32 s77, s77, 192
	s_and_b32 s77, s77, 255
	s_cmp_gt_u32 s77, 63
	s_cselect_b64 s[38:39], -1, 0
	s_mov_b64 s[20:21], 0
	v_mov_b32_e32 v8, v181
	s_movk_i32 s26, 0x400
	v_readfirstlane_b32 s3, v8
	s_and_b64 vcc, exec, s[38:39]
	s_cbranch_vccnz .LBB0_962
	s_ashr_i32 s0, s77, 31
	s_lshr_b32 s0, s0, 29
	s_add_i32 s2, s77, s0
	s_and_b32 s0, s2, -8
	s_sub_i32 s22, s77, s0
	s_cmp_gt_i32 s22, -1
	s_mov_b64 s[0:1], -1
	s_cbranch_scc0 .LBB0_959
	s_lshl_b32 s23, s22, 3
	s_mov_b64 s[0:1], 0

.LBB0_1020:
	v_readlane_b32 s77, v254, 56
	v_mov_b32_e32 v8, v181
	s_cmpk_lt_i32 s77, 0xa00
	s_movk_i32 s22, 0x400
	v_readfirstlane_b32 s26, v8
	s_cselect_b64 s[2:3], -1, 0
	s_cmpk_gt_i32 s77, 0x9ff
	s_cbranch_scc1 .LBB0_1022
	s_ashr_i32 s0, s77, 31
	s_lshr_b32 s0, s0, 29
	s_add_i32 s0, s77, s0
	s_ashr_i32 s1, s0, 3
	s_and_b32 s0, s0, -8
	s_sub_i32 s0, s77, s0
	s_cmp_lt_i32 s0, 0
	s_movk_i32 s20, 0x141
	s_cselect_b32 s20, s20, 0x140
	s_mul_i32 s0, s0, s20
	s_add_i32 s0, s0, s1
	s_mul_hi_i32 s1, s0, 0x66666667
	s_lshr_b32 s20, s1, 31
	s_ashr_i32 s1, s1, 10
	s_add_i32 s1, s1, s20
	s_mulk_i32 s1, 0xa00
	s_sub_i32 s0, s0, s1
	s_mul_i32 s1, s0, 0x6667
	s_lshr_b32 s20, s1, 31
	s_ashr_i32 s1, s1, 21
	s_add_i32 s1, s1, s20
	s_lshl_b32 s20, s1, 3
	s_mulk_i32 s1, 0x50
	s_sub_i32 s0, s0, s1
	s_bfe_i32 s1, s0, 0x80000
	s_bfe_u32 s1, s1, 0x3000c
	s_add_i32 s1, s0, s1
	s_and_b32 s21, s1, 0xf8
	s_sub_i32 s0, s0, s21
	s_bfe_i32 s1, s1, 0x80000
	s_sext_i32_i8 s0, s0
	s_sext_i32_i16 s1, s1
	s_add_i32 s0, s20, s0
	s_ashr_i32 s46, s1, 3

.Ltr_cont_1081:
	s_waitcnt lgkmcnt(0)
	ds_read2_b32 v[12:13], v43 offset1:8
	ds_read2_b32 v[84:85], v43 offset0:33 offset1:41
	ds_read2_b32 v[86:87], v43 offset0:66 offset1:74
	v_ashrrev_i32_e32 v9, 31, v8
	ds_read2_b32 v[88:89], v43 offset0:99 offset1:107
	v_lshl_add_u64 v[82:83], v[8:9], 1, v[6:7]
	s_waitcnt lgkmcnt(0)
	ds_read2_b32 v[90:91], v43 offset0:132 offset1:140
	ds_read2_b32 v[92:93], v43 offset0:165 offset1:173
	v_cvt_pk_bf16_f32 v8, v12, v84
	ds_read2_b32 v[94:95], v43 offset0:198 offset1:206
	ds_read2_b32 v[96:97], v43 offset0:231 offset1:239
	v_cvt_pk_bf16_f32 v9, v86, v88
	s_waitcnt lgkmcnt(0)
	v_cvt_pk_bf16_f32 v10, v90, v92
	v_add3_u32 v98, v42, v79, v81
	v_ashrrev_i32_e32 v99, 31, v98
	v_lshlrev_b64 v[100:101], 11, v[98:99]
	v_cvt_pk_bf16_f32 v11, v94, v96
	v_lshl_add_u64 v[100:101], v[82:83], 0, v[100:101]
	global_store_dwordx4 v[100:101], v[8:11], off
	s_nop 1
	v_cvt_pk_bf16_f32 v8, v13, v85
	v_cvt_pk_bf16_f32 v9, v87, v89
	v_cvt_pk_bf16_f32 v10, v91, v93
	v_cvt_pk_bf16_f32 v11, v95, v97
	v_add_u32_e32 v12, 8, v98
	v_ashrrev_i32_e32 v13, 31, v12
	v_lshlrev_b64 v[12:13], 11, v[12:13]
	ds_read2_b32 v[84:85], v43 offset0:16 offset1:24
	v_lshl_add_u64 v[12:13], v[82:83], 0, v[12:13]
	global_store_dwordx4 v[12:13], v[8:11], off
	ds_read2_b32 v[12:13], v43 offset0:49 offset1:57
	ds_read2_b32 v[86:87], v43 offset0:82 offset1:90
	ds_read2_b32 v[88:89], v43 offset0:115 offset1:123
	s_waitcnt lgkmcnt(0)
	ds_read2_b32 v[90:91], v43 offset0:148 offset1:156
	ds_read2_b32 v[92:93], v43 offset0:181 offset1:189
	v_cvt_pk_bf16_f32 v8, v84, v12
	ds_read2_b32 v[94:95], v43 offset0:214 offset1:222
	ds_read2_b32 v[96:97], v43 offset0:247 offset1:255
	v_cvt_pk_bf16_f32 v9, v86, v88
	s_waitcnt lgkmcnt(0)
	v_cvt_pk_bf16_f32 v10, v90, v92
	v_add_u32_e32 v100, 16, v98
	v_ashrrev_i32_e32 v101, 31, v100
	v_lshlrev_b64 v[100:101], 11, v[100:101]
	v_cvt_pk_bf16_f32 v11, v94, v96
	v_lshl_add_u64 v[100:101], v[82:83], 0, v[100:101]
	global_store_dwordx4 v[100:101], v[8:11], off
	s_nop 1
	v_cvt_pk_bf16_f32 v8, v85, v13
	v_cvt_pk_bf16_f32 v9, v87, v89
	v_cvt_pk_bf16_f32 v10, v91, v93
	v_cvt_pk_bf16_f32 v11, v95, v97
	v_add_u32_e32 v12, 24, v98
	v_ashrrev_i32_e32 v13, 31, v12
	v_lshlrev_b64 v[12:13], 11, v[12:13]
	v_lshl_add_u64 v[12:13], v[82:83], 0, v[12:13]
	global_store_dwordx4 v[12:13], v[8:11], off
	s_waitcnt lgkmcnt(0)
	v_add_u32_e32 v80, s22, v80
	s_movk_i32 s46, 0x4ff
	v_cmp_lt_i32_e32 vcc, s46, v80
	s_or_b64 s[50:51], vcc, s[50:51]
	v_add_u32_e32 v79, s23, v79
	s_andn2_b64 exec, exec, s[50:51]
	s_cbranch_execz .LBB0_1208
.LBB0_1081:
	s_mov_b32 s46, 0x66666667
	v_mul_hi_i32 v8, v80, s46
	v_lshrrev_b32_e32 v9, 31, v8
	v_ashrrev_i32_e32 v8, 5, v8
	v_add_u32_e32 v8, v8, v9
	s_movk_i32 s46, 0xf600
	v_mul_lo_u32 v81, v8, s46
	v_add3_u32 v10, v5, v79, v81
	s_movk_i32 s46, 0x90f
	v_cmp_lt_i32_e64 s[48:49], s46, v10
	v_lshlrev_b32_e32 v8, 6, v8
	v_ashrrev_i32_e32 v11, 31, v10
	v_lshl_add_u64 v[10:11], v[10:11], 2, s[26:27]
	v_or_b32_e32 v134, v8, v2
	v_mad_i64_i32 v[166:167], s[54:55], v134, s36, v[10:11]
	s_mov_b32 s100, 0x4880
	s_mov_b32 s101, 0
	v_mov_b64_e32 v[102:103], 0
	v_mov_b64_e32 v[104:105], 0
	v_mov_b64_e32 v[106:107], 0
	v_mov_b64_e32 v[108:109], 0
	v_mov_b64_e32 v[110:111], 0
	v_mov_b64_e32 v[112:113], 0
	v_mov_b64_e32 v[114:115], 0
	v_mov_b64_e32 v[116:117], 0
	v_mov_b64_e32 v[118:119], 0
	v_mov_b64_e32 v[120:121], 0
	v_mov_b64_e32 v[122:123], 0
	v_mov_b64_e32 v[124:125], 0
	v_mov_b64_e32 v[126:127], 0
	v_mov_b64_e32 v[128:129], 0
	v_mov_b64_e32 v[130:131], 0
	v_mov_b64_e32 v[132:133], 0
	s_mov_b64 s[54:55], exec
	s_andn2_b64 exec, exec, s[48:49]
	s_cbranch_execz .Ltr_skip_1081
	global_load_dword v102, v[166:167], off
	v_lshl_add_u64 v[166:167], v[166:167], 0, s[100:101]
	global_load_dword v103, v[166:167], off
	v_lshl_add_u64 v[166:167], v[166:167], 0, s[100:101]
	global_load_dword v104, v[166:167], off
	v_lshl_add_u64 v[166:167], v[166:167], 0, s[100:101]
	global_load_dword v105, v[166:167], off
	v_lshl_add_u64 v[166:167], v[166:167], 0, s[100:101]
	global_load_dword v106, v[166:167], off
	v_lshl_add_u64 v[166:167], v[166:167], 0, s[100:101]
	global_load_dword v107, v[166:167], off
	v_lshl_add_u64 v[166:167], v[166:167], 0, s[100:101]
	global_load_dword v108, v[166:167], off
	v_lshl_add_u64 v[166:167], v[166:167], 0, s[100:101]
	global_load_dword v109, v[166:167], off
	v_lshl_add_u64 v[166:167], v[166:167], 0, s[100:101]
	global_load_dword v110, v[166:167], off
	v_lshl_add_u64 v[166:167], v[166:167], 0, s[100:101]
	global_load_dword v111, v[166:167], off
	v_lshl_add_u64 v[166:167], v[166:167], 0, s[100:101]
	global_load_dword v112, v[166:167], off
	v_lshl_add_u64 v[166:167], v[166:167], 0, s[100:101]
	global_load_dword v113, v[166:167], off
	v_lshl_add_u64 v[166:167], v[166:167], 0, s[100:101]
	global_load_dword v114, v[166:167], off
	v_lshl_add_u64 v[166:167], v[166:167], 0, s[100:101]
	global_load_dword v115, v[166:167], off
	v_lshl_add_u64 v[166:167], v[166:167], 0, s[100:101]
	global_load_dword v116, v[166:167], off
	v_lshl_add_u64 v[166:167], v[166:167], 0, s[100:101]
	global_load_dword v117, v[166:167], off
	v_lshl_add_u64 v[166:167], v[166:167], 0, s[100:101]
	global_load_dword v118, v[166:167], off
	v_lshl_add_u64 v[166:167], v[166:167], 0, s[100:101]
	global_load_dword v119, v[166:167], off
	v_lshl_add_u64 v[166:167], v[166:167], 0, s[100:101]
	global_load_dword v120, v[166:167], off
	v_lshl_add_u64 v[166:167], v[166:167], 0, s[100:101]
	global_load_dword v121, v[166:167], off
	v_lshl_add_u64 v[166:167], v[166:167], 0, s[100:101]
	global_load_dword v122, v[166:167], off
	v_lshl_add_u64 v[166:167], v[166:167], 0, s[100:101]
	global_load_dword v123, v[166:167], off
	v_lshl_add_u64 v[166:167], v[166:167], 0, s[100:101]
	global_load_dword v124, v[166:167], off
	v_lshl_add_u64 v[166:167], v[166:167], 0, s[100:101]
	global_load_dword v125, v[166:167], off
	v_lshl_add_u64 v[166:167], v[166:167], 0, s[100:101]
	global_load_dword v126, v[166:167], off
	v_lshl_add_u64 v[166:167], v[166:167], 0, s[100:101]
	global_load_dword v127, v[166:167], off
	v_lshl_add_u64 v[166:167], v[166:167], 0, s[100:101]
	global_load_dword v128, v[166:167], off
	v_lshl_add_u64 v[166:167], v[166:167], 0, s[100:101]
	global_load_dword v129, v[166:167], off
	v_lshl_add_u64 v[166:167], v[166:167], 0, s[100:101]
	global_load_dword v130, v[166:167], off
	v_lshl_add_u64 v[166:167], v[166:167], 0, s[100:101]
	global_load_dword v131, v[166:167], off
	v_lshl_add_u64 v[166:167], v[166:167], 0, s[100:101]
	global_load_dword v132, v[166:167], off
	v_lshl_add_u64 v[166:167], v[166:167], 0, s[100:101]
	global_load_dword v133, v[166:167], off
.Ltr_skip_1081:
	s_mov_b64 exec, s[54:55]
	s_and_b64 vcc, exec, s[52:53]
	s_cbranch_vccz .Ltr_nors_1081
	v_ashrrev_i32_e32 v135, 31, v134
	v_lshl_add_u64 v[166:167], v[134:135], 2, s[20:21]
	global_load_dword v134, v[166:167], off offset:0
	global_load_dword v135, v[166:167], off offset:8
	global_load_dword v136, v[166:167], off offset:16
	global_load_dword v137, v[166:167], off offset:24
	global_load_dword v138, v[166:167], off offset:32
	global_load_dword v139, v[166:167], off offset:40
	global_load_dword v140, v[166:167], off offset:48
	global_load_dword v141, v[166:167], off offset:56
	global_load_dword v142, v[166:167], off offset:64
	global_load_dword v143, v[166:167], off offset:72
	global_load_dword v144, v[166:167], off offset:80
	global_load_dword v145, v[166:167], off offset:88
	global_load_dword v146, v[166:167], off offset:96
	global_load_dword v147, v[166:167], off offset:104
	global_load_dword v148, v[166:167], off offset:112
	global_load_dword v149, v[166:167], off offset:120
	global_load_dword v150, v[166:167], off offset:128
	global_load_dword v151, v[166:167], off offset:136
	global_load_dword v152, v[166:167], off offset:144
	global_load_dword v153, v[166:167], off offset:152
	global_load_dword v154, v[166:167], off offset:160
	global_load_dword v155, v[166:167], off offset:168
	global_load_dword v156, v[166:167], off offset:176
	global_load_dword v157, v[166:167], off offset:184
	global_load_dword v158, v[166:167], off offset:192
	global_load_dword v159, v[166:167], off offset:200
	global_load_dword v160, v[166:167], off offset:208
	global_load_dword v161, v[166:167], off offset:216
	global_load_dword v162, v[166:167], off offset:224
	global_load_dword v163, v[166:167], off offset:232
	global_load_dword v164, v[166:167], off offset:240
	global_load_dword v165, v[166:167], off offset:248
	s_waitcnt vmcnt(0)
	v_mul_f32_e32 v102, v102, v134
	v_mul_f32_e32 v103, v103, v135
	v_mul_f32_e32 v104, v104, v136
	v_mul_f32_e32 v105, v105, v137
	v_mul_f32_e32 v106, v106, v138
	v_mul_f32_e32 v107, v107, v139
	v_mul_f32_e32 v108, v108, v140
	v_mul_f32_e32 v109, v109, v141
	v_mul_f32_e32 v110, v110, v142
	v_mul_f32_e32 v111, v111, v143
	v_mul_f32_e32 v112, v112, v144
	v_mul_f32_e32 v113, v113, v145
	v_mul_f32_e32 v114, v114, v146
	v_mul_f32_e32 v115, v115, v147
	v_mul_f32_e32 v116, v116, v148
	v_mul_f32_e32 v117, v117, v149
	v_mul_f32_e32 v118, v118, v150
	v_mul_f32_e32 v119, v119, v151
	v_mul_f32_e32 v120, v120, v152
	v_mul_f32_e32 v121, v121, v153
	v_mul_f32_e32 v122, v122, v154
	v_mul_f32_e32 v123, v123, v155
	v_mul_f32_e32 v124, v124, v156
	v_mul_f32_e32 v125, v125, v157
	v_mul_f32_e32 v126, v126, v158
	v_mul_f32_e32 v127, v127, v159
	v_mul_f32_e32 v128, v128, v160
	v_mul_f32_e32 v129, v129, v161
	v_mul_f32_e32 v130, v130, v162
	v_mul_f32_e32 v131, v131, v163
	v_mul_f32_e32 v132, v132, v164
	v_mul_f32_e32 v133, v133, v165
	s_branch .Ltr_wr_1081

.Ltr_wr_1081:
	v_add_u32_e32 v166, v16, v17
	ds_write_b32 v166, v102 offset:0
	ds_write_b32 v166, v103 offset:264
	ds_write_b32 v166, v104 offset:528
	ds_write_b32 v166, v105 offset:792
	ds_write_b32 v166, v106 offset:1056
	ds_write_b32 v166, v107 offset:1320
	ds_write_b32 v166, v108 offset:1584
	ds_write_b32 v166, v109 offset:1848
	ds_write_b32 v166, v110 offset:2112
	ds_write_b32 v166, v111 offset:2376
	ds_write_b32 v166, v112 offset:2640
	ds_write_b32 v166, v113 offset:2904
	ds_write_b32 v166, v114 offset:3168
	ds_write_b32 v166, v115 offset:3432
	ds_write_b32 v166, v116 offset:3696
	ds_write_b32 v166, v117 offset:3960
	ds_write_b32 v166, v118 offset:4224
	ds_write_b32 v166, v119 offset:4488
	ds_write_b32 v166, v120 offset:4752
	ds_write_b32 v166, v121 offset:5016
	ds_write_b32 v166, v122 offset:5280
	ds_write_b32 v166, v123 offset:5544
	ds_write_b32 v166, v124 offset:5808
	ds_write_b32 v166, v125 offset:6072
	ds_write_b32 v166, v126 offset:6336
	ds_write_b32 v166, v127 offset:6600
	ds_write_b32 v166, v128 offset:6864
	ds_write_b32 v166, v129 offset:7128
	ds_write_b32 v166, v130 offset:7392
	ds_write_b32 v166, v131 offset:7656
	ds_write_b32 v166, v132 offset:7920
	ds_write_b32 v166, v133 offset:8184
	s_branch .Ltr_cont_1081
.LBB0_1208:
	s_or_b64 exec, exec, s[24:25]
	s_xor_b64 s[24:25], s[2:3], -1
	s_mov_b64 s[20:21], 0
	s_lshl_b64 s[50:51], s[34:35], 20
	v_add_u32_e32 v170, 0x300, v28
	v_cmp_le_i32_e32 vcc, s22, v170
	v_subrev_u32_e32 v174, s22, v170
	s_nop 0
	v_cndmask_b32_e32 v170, v170, v174, vcc
	v_cmp_gt_i32_e32 vcc, 0x200, v170
	s_and_saveexec_b64 s[2:3], vcc
	s_cbranch_execz .LBB0_1243
	s_add_u32 s23, s92, s20
	s_addc_u32 s26, s93, s21
	s_lshl_b64 s[20:21], s[50:51], 2
	s_add_u32 s20, s23, s20
	s_addc_u32 s21, s26, s21
	v_lshl_add_u64 v[6:7], s[0:1], 0, v[168:169]
	s_mov_b64 s[26:27], 0x500000
	v_lshl_add_u64 v[6:7], v[6:7], 0, s[26:27]
	v_lshlrev_b32_e32 v12, 5, v170
	s_lshl_b32 s23, s22, 5
	s_mov_b64 s[26:27], 0
	v_mov_b32_e32 v13, v170
	s_branch .LBB0_1211
.Ltr_cont_1211:
	s_waitcnt lgkmcnt(0)
	ds_read2_b32 v[80:81], v43 offset1:8
	ds_read2_b32 v[84:85], v43 offset0:33 offset1:41
	ds_read2_b32 v[86:87], v43 offset0:66 offset1:74
	v_sub_u32_e32 v79, 0, v9
	v_ashrrev_i32_e32 v9, 31, v8
	ds_read2_b32 v[88:89], v43 offset0:99 offset1:107
	v_lshl_add_u64 v[82:83], v[8:9], 1, v[6:7]
	s_waitcnt lgkmcnt(0)
	ds_read2_b32 v[90:91], v43 offset0:132 offset1:140
	ds_read2_b32 v[92:93], v43 offset0:165 offset1:173
	v_cvt_pk_bf16_f32 v8, v80, v84
	ds_read2_b32 v[94:95], v43 offset0:198 offset1:206
	ds_read2_b32 v[96:97], v43 offset0:231 offset1:239
	v_cvt_pk_bf16_f32 v9, v86, v88
	s_waitcnt lgkmcnt(0)
	v_cvt_pk_bf16_f32 v10, v90, v92
	v_add3_u32 v98, v42, v12, v79
	v_ashrrev_i32_e32 v99, 31, v98
	v_lshlrev_b64 v[100:101], 11, v[98:99]
	v_cvt_pk_bf16_f32 v11, v94, v96
	v_lshl_add_u64 v[100:101], v[82:83], 0, v[100:101]
	global_store_dwordx4 v[100:101], v[8:11], off
	v_add_u32_e32 v80, 8, v98
	s_nop 0
	v_cvt_pk_bf16_f32 v8, v81, v85
	v_cvt_pk_bf16_f32 v9, v87, v89
	v_cvt_pk_bf16_f32 v10, v91, v93
	v_ashrrev_i32_e32 v81, 31, v80
	v_lshlrev_b64 v[80:81], 11, v[80:81]
	v_cvt_pk_bf16_f32 v11, v95, v97
	ds_read2_b32 v[84:85], v43 offset0:16 offset1:24
	v_lshl_add_u64 v[80:81], v[82:83], 0, v[80:81]
	global_store_dwordx4 v[80:81], v[8:11], off
	ds_read2_b32 v[80:81], v43 offset0:49 offset1:57
	ds_read2_b32 v[86:87], v43 offset0:82 offset1:90
	ds_read2_b32 v[88:89], v43 offset0:115 offset1:123
	s_waitcnt lgkmcnt(0)
	ds_read2_b32 v[90:91], v43 offset0:148 offset1:156
	ds_read2_b32 v[92:93], v43 offset0:181 offset1:189
	v_cvt_pk_bf16_f32 v8, v84, v80
	ds_read2_b32 v[94:95], v43 offset0:214 offset1:222
	ds_read2_b32 v[96:97], v43 offset0:247 offset1:255
	v_cvt_pk_bf16_f32 v9, v86, v88
	s_waitcnt lgkmcnt(0)
	v_cvt_pk_bf16_f32 v10, v90, v92
	v_add_u32_e32 v100, 16, v98
	v_ashrrev_i32_e32 v101, 31, v100
	v_lshlrev_b64 v[100:101], 11, v[100:101]
	v_cvt_pk_bf16_f32 v11, v94, v96
	v_lshl_add_u64 v[100:101], v[82:83], 0, v[100:101]
	global_store_dwordx4 v[100:101], v[8:11], off
	v_add_u32_e32 v80, 24, v98
	s_nop 0
	v_cvt_pk_bf16_f32 v8, v85, v81
	v_cvt_pk_bf16_f32 v9, v87, v89
	v_cvt_pk_bf16_f32 v10, v91, v93
	v_ashrrev_i32_e32 v81, 31, v80
	v_lshlrev_b64 v[80:81], 11, v[80:81]
	v_cvt_pk_bf16_f32 v11, v95, v97
	v_lshl_add_u64 v[80:81], v[82:83], 0, v[80:81]
	global_store_dwordx4 v[80:81], v[8:11], off
	s_waitcnt lgkmcnt(0)
	v_add_u32_e32 v13, s22, v13
	v_cmp_lt_i32_e32 vcc, s31, v13
	s_or_b64 s[26:27], vcc, s[26:27]
	v_add_u32_e32 v12, s23, v12
	s_andn2_b64 exec, exec, s[26:27]
	s_cbranch_execz .LBB0_1243
.LBB0_1211:
	v_ashrrev_i32_e32 v8, 31, v13
	v_lshrrev_b32_e32 v8, 27, v8
	v_add_u32_e32 v8, v13, v8
	v_ashrrev_i32_e32 v8, 5, v8
	v_lshlrev_b32_e32 v9, 10, v8
	v_add_u32_e32 v10, v5, v12
	v_sub_u32_e32 v10, v10, v9
	v_cmp_lt_i32_e32 vcc, s33, v10
	v_lshlrev_b32_e32 v8, 6, v8
	v_ashrrev_i32_e32 v11, 31, v10
	v_lshl_add_u64 v[10:11], v[10:11], 2, s[20:21]
	v_or_b32_e32 v134, v8, v2
	v_ashrrev_i32_e32 v135, 31, v134
	v_lshlrev_b64 v[166:167], 12, v[134:135]
	v_lshl_add_u64 v[166:167], v[10:11], 0, v[166:167]
	s_mov_b32 s100, 0x2000
	s_mov_b32 s101, 0
	v_mov_b64_e32 v[102:103], 0
	v_mov_b64_e32 v[104:105], 0
	v_mov_b64_e32 v[106:107], 0
	v_mov_b64_e32 v[108:109], 0
	v_mov_b64_e32 v[110:111], 0
	v_mov_b64_e32 v[112:113], 0
	v_mov_b64_e32 v[114:115], 0
	v_mov_b64_e32 v[116:117], 0
	v_mov_b64_e32 v[118:119], 0
	v_mov_b64_e32 v[120:121], 0
	v_mov_b64_e32 v[122:123], 0
	v_mov_b64_e32 v[124:125], 0
	v_mov_b64_e32 v[126:127], 0
	v_mov_b64_e32 v[128:129], 0
	v_mov_b64_e32 v[130:131], 0
	v_mov_b64_e32 v[132:133], 0
	s_mov_b64 s[46:47], exec
	s_andn2_b64 exec, exec, vcc
	s_cbranch_execz .Ltr_skip_1211
	global_load_dword v102, v[166:167], off
	v_lshl_add_u64 v[166:167], v[166:167], 0, s[100:101]
	global_load_dword v103, v[166:167], off
	v_lshl_add_u64 v[166:167], v[166:167], 0, s[100:101]
	global_load_dword v104, v[166:167], off
	v_lshl_add_u64 v[166:167], v[166:167], 0, s[100:101]
	global_load_dword v105, v[166:167], off
	v_lshl_add_u64 v[166:167], v[166:167], 0, s[100:101]
	global_load_dword v106, v[166:167], off
	v_lshl_add_u64 v[166:167], v[166:167], 0, s[100:101]
	global_load_dword v107, v[166:167], off
	v_lshl_add_u64 v[166:167], v[166:167], 0, s[100:101]
	global_load_dword v108, v[166:167], off
	v_lshl_add_u64 v[166:167], v[166:167], 0, s[100:101]
	global_load_dword v109, v[166:167], off
	v_lshl_add_u64 v[166:167], v[166:167], 0, s[100:101]
	global_load_dword v110, v[166:167], off
	v_lshl_add_u64 v[166:167], v[166:167], 0, s[100:101]
	global_load_dword v111, v[166:167], off
	v_lshl_add_u64 v[166:167], v[166:167], 0, s[100:101]
	global_load_dword v112, v[166:167], off
	v_lshl_add_u64 v[166:167], v[166:167], 0, s[100:101]
	global_load_dword v113, v[166:167], off
	v_lshl_add_u64 v[166:167], v[166:167], 0, s[100:101]
	global_load_dword v114, v[166:167], off
	v_lshl_add_u64 v[166:167], v[166:167], 0, s[100:101]
	global_load_dword v115, v[166:167], off
	v_lshl_add_u64 v[166:167], v[166:167], 0, s[100:101]
	global_load_dword v116, v[166:167], off
	v_lshl_add_u64 v[166:167], v[166:167], 0, s[100:101]
	global_load_dword v117, v[166:167], off
	v_lshl_add_u64 v[166:167], v[166:167], 0, s[100:101]
	global_load_dword v118, v[166:167], off
	v_lshl_add_u64 v[166:167], v[166:167], 0, s[100:101]
	global_load_dword v119, v[166:167], off
	v_lshl_add_u64 v[166:167], v[166:167], 0, s[100:101]
	global_load_dword v120, v[166:167], off
	v_lshl_add_u64 v[166:167], v[166:167], 0, s[100:101]
	global_load_dword v121, v[166:167], off
	v_lshl_add_u64 v[166:167], v[166:167], 0, s[100:101]
	global_load_dword v122, v[166:167], off
	v_lshl_add_u64 v[166:167], v[166:167], 0, s[100:101]
	global_load_dword v123, v[166:167], off
	v_lshl_add_u64 v[166:167], v[166:167], 0, s[100:101]
	global_load_dword v124, v[166:167], off
	v_lshl_add_u64 v[166:167], v[166:167], 0, s[100:101]
	global_load_dword v125, v[166:167], off
	v_lshl_add_u64 v[166:167], v[166:167], 0, s[100:101]
	global_load_dword v126, v[166:167], off
	v_lshl_add_u64 v[166:167], v[166:167], 0, s[100:101]
	global_load_dword v127, v[166:167], off
	v_lshl_add_u64 v[166:167], v[166:167], 0, s[100:101]
	global_load_dword v128, v[166:167], off
	v_lshl_add_u64 v[166:167], v[166:167], 0, s[100:101]
	global_load_dword v129, v[166:167], off
	v_lshl_add_u64 v[166:167], v[166:167], 0, s[100:101]
	global_load_dword v130, v[166:167], off
	v_lshl_add_u64 v[166:167], v[166:167], 0, s[100:101]
	global_load_dword v131, v[166:167], off
	v_lshl_add_u64 v[166:167], v[166:167], 0, s[100:101]
	global_load_dword v132, v[166:167], off
	v_lshl_add_u64 v[166:167], v[166:167], 0, s[100:101]
	global_load_dword v133, v[166:167], off
.Ltr_skip_1211:
	s_mov_b64 exec, s[46:47]
	s_waitcnt vmcnt(0)
	v_add_u32_e32 v166, v16, v17
	ds_write_b32 v166, v102 offset:0
	ds_write_b32 v166, v103 offset:264
	ds_write_b32 v166, v104 offset:528
	ds_write_b32 v166, v105 offset:792
	ds_write_b32 v166, v106 offset:1056
	ds_write_b32 v166, v107 offset:1320
	ds_write_b32 v166, v108 offset:1584
	ds_write_b32 v166, v109 offset:1848
	ds_write_b32 v166, v110 offset:2112
	ds_write_b32 v166, v111 offset:2376
	ds_write_b32 v166, v112 offset:2640
	ds_write_b32 v166, v113 offset:2904
	ds_write_b32 v166, v114 offset:3168
	ds_write_b32 v166, v115 offset:3432
	ds_write_b32 v166, v116 offset:3696
	ds_write_b32 v166, v117 offset:3960
	ds_write_b32 v166, v118 offset:4224
	ds_write_b32 v166, v119 offset:4488
	ds_write_b32 v166, v120 offset:4752
	ds_write_b32 v166, v121 offset:5016
	ds_write_b32 v166, v122 offset:5280
	ds_write_b32 v166, v123 offset:5544
	ds_write_b32 v166, v124 offset:5808
	ds_write_b32 v166, v125 offset:6072
	ds_write_b32 v166, v126 offset:6336
	ds_write_b32 v166, v127 offset:6600
	ds_write_b32 v166, v128 offset:6864
	ds_write_b32 v166, v129 offset:7128
	ds_write_b32 v166, v130 offset:7392
	ds_write_b32 v166, v131 offset:7656
	ds_write_b32 v166, v132 offset:7920
	ds_write_b32 v166, v133 offset:8184
	s_branch .Ltr_cont_1211
.LBB0_1243:
	s_or_b64 exec, exec, s[2:3]
	s_mov_b64 s[20:21], 0
	s_mov_b64 s[46:47], 0
	s_lshl_b32 s26, s34, 10
	s_mov_b32 s27, s35
	v_add_u32_e32 v170, 0x100, v28
	v_cmp_le_i32_e32 vcc, s22, v170
	v_subrev_u32_e32 v174, s22, v170
	s_nop 0
	v_cndmask_b32_e32 v170, v170, v174, vcc
	v_cmp_gt_i32_e32 vcc, 0x200, v170
	s_and_saveexec_b64 s[2:3], vcc
	s_cbranch_execz .LBB0_1374
	v_readlane_b32 s52, v252, 16
	v_readlane_b32 s54, v252, 18
	v_readlane_b32 s55, v252, 19
	s_add_u32 s23, s54, s20
	s_addc_u32 s48, s55, s21
	s_lshl_b64 s[20:21], s[50:51], 2
	s_add_u32 s20, s23, s20
	s_addc_u32 s21, s48, s21
	s_add_u32 s23, s94, s46
	s_addc_u32 s48, s95, s47
	s_lshl_b64 s[46:47], s[26:27], 2
	v_readlane_b32 s53, v252, 17
	s_add_u32 s52, s23, s46
	s_addc_u32 s53, s48, s47
	v_lshl_add_u64 v[6:7], s[0:1], 0, v[168:169]
	s_mov_b64 s[46:47], 0x700000
	v_lshl_add_u64 v[6:7], v[6:7], 0, s[46:47]
	v_lshlrev_b32_e32 v79, 5, v170
	s_lshl_b32 s23, s22, 5
	s_mov_b64 s[54:55], 0
	v_mov_b32_e32 v80, v170
	v_readlane_b32 s56, v252, 20
	v_readlane_b32 s57, v252, 21
	v_readlane_b32 s58, v252, 22
	v_readlane_b32 s59, v252, 23
	v_readlane_b32 s60, v252, 24
	v_readlane_b32 s61, v252, 25
	v_readlane_b32 s62, v252, 26
	v_readlane_b32 s63, v252, 27
	v_readlane_b32 s64, v252, 28
	v_readlane_b32 s65, v252, 29
	v_readlane_b32 s66, v252, 30
	v_readlane_b32 s67, v252, 31
	s_branch .LBB0_1247
.Ltr_cont_1247:
	s_waitcnt lgkmcnt(0)
	ds_read2_b32 v[82:83], v43 offset1:8
	ds_read2_b32 v[86:87], v43 offset0:33 offset1:41
	ds_read2_b32 v[88:89], v43 offset0:66 offset1:74
	v_ashrrev_i32_e32 v9, 31, v8
	ds_read2_b32 v[90:91], v43 offset0:99 offset1:107
	v_lshl_add_u64 v[84:85], v[8:9], 1, v[6:7]
	s_waitcnt lgkmcnt(0)
	ds_read2_b32 v[92:93], v43 offset0:132 offset1:140
	ds_read2_b32 v[94:95], v43 offset0:165 offset1:173
	v_cvt_pk_bf16_f32 v8, v82, v86
	ds_read2_b32 v[96:97], v43 offset0:198 offset1:206
	ds_read2_b32 v[98:99], v43 offset0:231 offset1:239
	v_cvt_pk_bf16_f32 v9, v88, v90
	s_waitcnt lgkmcnt(0)
	v_cvt_pk_bf16_f32 v10, v92, v94
	v_add3_u32 v12, v42, v79, v12
	v_cvt_pk_bf16_f32 v11, v96, v98
	v_ashrrev_i32_e32 v13, 31, v12
	v_lshlrev_b64 v[100:101], 11, v[12:13]
	v_lshl_add_u64 v[100:101], v[84:85], 0, v[100:101]
	global_store_dwordx4 v[100:101], v[8:11], off
	v_add_u32_e32 v82, 8, v12
	s_nop 0
	v_cvt_pk_bf16_f32 v8, v83, v87
	v_cvt_pk_bf16_f32 v9, v89, v91
	v_cvt_pk_bf16_f32 v10, v93, v95
	v_ashrrev_i32_e32 v83, 31, v82
	v_lshlrev_b64 v[82:83], 11, v[82:83]
	v_cvt_pk_bf16_f32 v11, v97, v99
	ds_read2_b32 v[86:87], v43 offset0:16 offset1:24
	v_lshl_add_u64 v[82:83], v[84:85], 0, v[82:83]
	global_store_dwordx4 v[82:83], v[8:11], off
	ds_read2_b32 v[82:83], v43 offset0:49 offset1:57
	ds_read2_b32 v[88:89], v43 offset0:82 offset1:90
	ds_read2_b32 v[90:91], v43 offset0:115 offset1:123
	s_waitcnt lgkmcnt(0)
	ds_read2_b32 v[92:93], v43 offset0:148 offset1:156
	ds_read2_b32 v[94:95], v43 offset0:181 offset1:189
	v_cvt_pk_bf16_f32 v8, v86, v82
	ds_read2_b32 v[96:97], v43 offset0:214 offset1:222
	ds_read2_b32 v[98:99], v43 offset0:247 offset1:255
	v_cvt_pk_bf16_f32 v9, v88, v90
	s_waitcnt lgkmcnt(0)
	v_cvt_pk_bf16_f32 v10, v92, v94
	v_add_u32_e32 v100, 16, v12
	v_ashrrev_i32_e32 v101, 31, v100
	v_lshlrev_b64 v[100:101], 11, v[100:101]
	v_cvt_pk_bf16_f32 v11, v96, v98
	v_lshl_add_u64 v[100:101], v[84:85], 0, v[100:101]
	global_store_dwordx4 v[100:101], v[8:11], off
	s_nop 1
	v_cvt_pk_bf16_f32 v8, v87, v83
	v_cvt_pk_bf16_f32 v9, v89, v91
	v_cvt_pk_bf16_f32 v10, v93, v95
	v_add_u32_e32 v12, 24, v12
	v_cvt_pk_bf16_f32 v11, v97, v99
	v_ashrrev_i32_e32 v13, 31, v12
	v_lshlrev_b64 v[12:13], 11, v[12:13]
	v_lshl_add_u64 v[12:13], v[84:85], 0, v[12:13]
	global_store_dwordx4 v[12:13], v[8:11], off
	s_waitcnt lgkmcnt(0)
	v_add_u32_e32 v80, s22, v80
	v_cmp_lt_i32_e32 vcc, s31, v80
	s_or_b64 s[54:55], vcc, s[54:55]
	v_add_u32_e32 v79, s23, v79
	s_andn2_b64 exec, exec, s[54:55]
	s_cbranch_execz .LBB0_1374
.LBB0_1247:
	v_ashrrev_i32_e32 v8, 31, v80
	v_lshrrev_b32_e32 v8, 27, v8
	v_add_u32_e32 v8, v80, v8
	v_ashrrev_i32_e32 v8, 5, v8
	v_lshlrev_b32_e32 v81, 10, v8
	v_add_u32_e32 v9, v5, v79
	v_sub_u32_e32 v10, v9, v81
	v_cmp_lt_i32_e64 s[48:49], s33, v10
	v_lshlrev_b32_e32 v8, 6, v8
	v_ashrrev_i32_e32 v11, 31, v10
	v_lshl_add_u64 v[10:11], v[10:11], 2, s[20:21]
	v_sub_u32_e32 v12, 0, v81
	v_or_b32_e32 v134, v8, v2
	v_ashrrev_i32_e32 v135, 31, v134
	v_lshlrev_b64 v[166:167], 12, v[134:135]
	v_lshl_add_u64 v[166:167], v[10:11], 0, v[166:167]
	s_mov_b32 s100, 0x2000
	s_mov_b32 s101, 0
	v_mov_b64_e32 v[102:103], 0
	v_mov_b64_e32 v[104:105], 0
	v_mov_b64_e32 v[106:107], 0
	v_mov_b64_e32 v[108:109], 0
	v_mov_b64_e32 v[110:111], 0
	v_mov_b64_e32 v[112:113], 0
	v_mov_b64_e32 v[114:115], 0
	v_mov_b64_e32 v[116:117], 0
	v_mov_b64_e32 v[118:119], 0
	v_mov_b64_e32 v[120:121], 0
	v_mov_b64_e32 v[122:123], 0
	v_mov_b64_e32 v[124:125], 0
	v_mov_b64_e32 v[126:127], 0
	v_mov_b64_e32 v[128:129], 0
	v_mov_b64_e32 v[130:131], 0
	v_mov_b64_e32 v[132:133], 0
	s_mov_b64 s[56:57], exec
	s_andn2_b64 exec, exec, s[48:49]
	s_cbranch_execz .Ltr_skip_1247
	global_load_dword v102, v[166:167], off
	v_lshl_add_u64 v[166:167], v[166:167], 0, s[100:101]
	global_load_dword v103, v[166:167], off
	v_lshl_add_u64 v[166:167], v[166:167], 0, s[100:101]
	global_load_dword v104, v[166:167], off
	v_lshl_add_u64 v[166:167], v[166:167], 0, s[100:101]
	global_load_dword v105, v[166:167], off
	v_lshl_add_u64 v[166:167], v[166:167], 0, s[100:101]
	global_load_dword v106, v[166:167], off
	v_lshl_add_u64 v[166:167], v[166:167], 0, s[100:101]
	global_load_dword v107, v[166:167], off
	v_lshl_add_u64 v[166:167], v[166:167], 0, s[100:101]
	global_load_dword v108, v[166:167], off
	v_lshl_add_u64 v[166:167], v[166:167], 0, s[100:101]
	global_load_dword v109, v[166:167], off
	v_lshl_add_u64 v[166:167], v[166:167], 0, s[100:101]
	global_load_dword v110, v[166:167], off
	v_lshl_add_u64 v[166:167], v[166:167], 0, s[100:101]
	global_load_dword v111, v[166:167], off
	v_lshl_add_u64 v[166:167], v[166:167], 0, s[100:101]
	global_load_dword v112, v[166:167], off
	v_lshl_add_u64 v[166:167], v[166:167], 0, s[100:101]
	global_load_dword v113, v[166:167], off
	v_lshl_add_u64 v[166:167], v[166:167], 0, s[100:101]
	global_load_dword v114, v[166:167], off
	v_lshl_add_u64 v[166:167], v[166:167], 0, s[100:101]
	global_load_dword v115, v[166:167], off
	v_lshl_add_u64 v[166:167], v[166:167], 0, s[100:101]
	global_load_dword v116, v[166:167], off
	v_lshl_add_u64 v[166:167], v[166:167], 0, s[100:101]
	global_load_dword v117, v[166:167], off
	v_lshl_add_u64 v[166:167], v[166:167], 0, s[100:101]
	global_load_dword v118, v[166:167], off
	v_lshl_add_u64 v[166:167], v[166:167], 0, s[100:101]
	global_load_dword v119, v[166:167], off
	v_lshl_add_u64 v[166:167], v[166:167], 0, s[100:101]
	global_load_dword v120, v[166:167], off
	v_lshl_add_u64 v[166:167], v[166:167], 0, s[100:101]
	global_load_dword v121, v[166:167], off
	v_lshl_add_u64 v[166:167], v[166:167], 0, s[100:101]
	global_load_dword v122, v[166:167], off
	v_lshl_add_u64 v[166:167], v[166:167], 0, s[100:101]
	global_load_dword v123, v[166:167], off
	v_lshl_add_u64 v[166:167], v[166:167], 0, s[100:101]
	global_load_dword v124, v[166:167], off
	v_lshl_add_u64 v[166:167], v[166:167], 0, s[100:101]
	global_load_dword v125, v[166:167], off
	v_lshl_add_u64 v[166:167], v[166:167], 0, s[100:101]
	global_load_dword v126, v[166:167], off
	v_lshl_add_u64 v[166:167], v[166:167], 0, s[100:101]
	global_load_dword v127, v[166:167], off
	v_lshl_add_u64 v[166:167], v[166:167], 0, s[100:101]
	global_load_dword v128, v[166:167], off
	v_lshl_add_u64 v[166:167], v[166:167], 0, s[100:101]
	global_load_dword v129, v[166:167], off
	v_lshl_add_u64 v[166:167], v[166:167], 0, s[100:101]
	global_load_dword v130, v[166:167], off
	v_lshl_add_u64 v[166:167], v[166:167], 0, s[100:101]
	global_load_dword v131, v[166:167], off
	v_lshl_add_u64 v[166:167], v[166:167], 0, s[100:101]
	global_load_dword v132, v[166:167], off
	v_lshl_add_u64 v[166:167], v[166:167], 0, s[100:101]
	global_load_dword v133, v[166:167], off
.Ltr_skip_1247:
	s_mov_b64 exec, s[56:57]
	v_readlane_b32 s46, v252, 14
	v_readlane_b32 s47, v252, 15
	s_and_b64 vcc, exec, s[46:47]
	s_cbranch_vccz .Ltr_nors_1247
	v_ashrrev_i32_e32 v135, 31, v134
	v_lshl_add_u64 v[166:167], v[134:135], 2, s[52:53]
	global_load_dword v134, v[166:167], off offset:0
	global_load_dword v135, v[166:167], off offset:8
	global_load_dword v136, v[166:167], off offset:16
	global_load_dword v137, v[166:167], off offset:24
	global_load_dword v138, v[166:167], off offset:32
	global_load_dword v139, v[166:167], off offset:40
	global_load_dword v140, v[166:167], off offset:48
	global_load_dword v141, v[166:167], off offset:56
	global_load_dword v142, v[166:167], off offset:64
	global_load_dword v143, v[166:167], off offset:72
	global_load_dword v144, v[166:167], off offset:80
	global_load_dword v145, v[166:167], off offset:88
	global_load_dword v146, v[166:167], off offset:96
	global_load_dword v147, v[166:167], off offset:104
	global_load_dword v148, v[166:167], off offset:112
	global_load_dword v149, v[166:167], off offset:120
	global_load_dword v150, v[166:167], off offset:128
	global_load_dword v151, v[166:167], off offset:136
	global_load_dword v152, v[166:167], off offset:144
	global_load_dword v153, v[166:167], off offset:152
	global_load_dword v154, v[166:167], off offset:160
	global_load_dword v155, v[166:167], off offset:168
	global_load_dword v156, v[166:167], off offset:176
	global_load_dword v157, v[166:167], off offset:184
	global_load_dword v158, v[166:167], off offset:192
	global_load_dword v159, v[166:167], off offset:200
	global_load_dword v160, v[166:167], off offset:208
	global_load_dword v161, v[166:167], off offset:216
	global_load_dword v162, v[166:167], off offset:224
	global_load_dword v163, v[166:167], off offset:232
	global_load_dword v164, v[166:167], off offset:240
	global_load_dword v165, v[166:167], off offset:248
	s_waitcnt vmcnt(0)
	v_mul_f32_e32 v102, v102, v134
	v_mul_f32_e32 v103, v103, v135
	v_mul_f32_e32 v104, v104, v136
	v_mul_f32_e32 v105, v105, v137
	v_mul_f32_e32 v106, v106, v138
	v_mul_f32_e32 v107, v107, v139
	v_mul_f32_e32 v108, v108, v140
	v_mul_f32_e32 v109, v109, v141
	v_mul_f32_e32 v110, v110, v142
	v_mul_f32_e32 v111, v111, v143
	v_mul_f32_e32 v112, v112, v144
	v_mul_f32_e32 v113, v113, v145
	v_mul_f32_e32 v114, v114, v146
	v_mul_f32_e32 v115, v115, v147
	v_mul_f32_e32 v116, v116, v148
	v_mul_f32_e32 v117, v117, v149
	v_mul_f32_e32 v118, v118, v150
	v_mul_f32_e32 v119, v119, v151
	v_mul_f32_e32 v120, v120, v152
	v_mul_f32_e32 v121, v121, v153
	v_mul_f32_e32 v122, v122, v154
	v_mul_f32_e32 v123, v123, v155
	v_mul_f32_e32 v124, v124, v156
	v_mul_f32_e32 v125, v125, v157
	v_mul_f32_e32 v126, v126, v158
	v_mul_f32_e32 v127, v127, v159
	v_mul_f32_e32 v128, v128, v160
	v_mul_f32_e32 v129, v129, v161
	v_mul_f32_e32 v130, v130, v162
	v_mul_f32_e32 v131, v131, v163
	v_mul_f32_e32 v132, v132, v164
	v_mul_f32_e32 v133, v133, v165
	s_branch .Ltr_wr_1247

.LBB0_1374:
	s_or_b64 exec, exec, s[2:3]
	s_mov_b64 s[20:21], 0
	v_add_u32_e32 v170, 0x700, v28
	v_cmp_le_i32_e32 vcc, s22, v170
	v_subrev_u32_e32 v174, s22, v170
	s_nop 0
	v_cndmask_b32_e32 v170, v170, v174, vcc
	v_cmp_gt_i32_e32 vcc, 0x200, v170
	s_and_saveexec_b64 s[2:3], vcc
	s_cbranch_execz .LBB0_1409
	v_readlane_b32 s52, v252, 16
	v_readlane_b32 s56, v252, 20
	v_readlane_b32 s57, v252, 21
	s_add_u32 s23, s56, s20
	s_addc_u32 s46, s57, s21
	s_lshl_b64 s[20:21], s[50:51], 2
	s_add_u32 s20, s23, s20
	s_addc_u32 s21, s46, s21
	v_lshl_add_u64 v[6:7], s[0:1], 0, v[168:169]
	s_mov_b64 s[46:47], 0x900000
	v_lshl_add_u64 v[6:7], v[6:7], 0, s[46:47]
	v_lshlrev_b32_e32 v12, 5, v170
	s_lshl_b32 s23, s22, 5
	s_mov_b64 s[46:47], 0
	v_mov_b32_e32 v13, v170
	v_readlane_b32 s53, v252, 17
	v_readlane_b32 s54, v252, 18
	v_readlane_b32 s55, v252, 19
	v_readlane_b32 s58, v252, 22
	v_readlane_b32 s59, v252, 23
	v_readlane_b32 s60, v252, 24
	v_readlane_b32 s61, v252, 25
	v_readlane_b32 s62, v252, 26
	v_readlane_b32 s63, v252, 27
	v_readlane_b32 s64, v252, 28
	v_readlane_b32 s65, v252, 29
	v_readlane_b32 s66, v252, 30
	v_readlane_b32 s67, v252, 31
	s_branch .LBB0_1377
.Ltr_cont_1377:
	s_waitcnt lgkmcnt(0)
	ds_read2_b32 v[80:81], v43 offset1:8
	ds_read2_b32 v[84:85], v43 offset0:33 offset1:41
	ds_read2_b32 v[86:87], v43 offset0:66 offset1:74
	v_sub_u32_e32 v79, 0, v9
	v_ashrrev_i32_e32 v9, 31, v8
	ds_read2_b32 v[88:89], v43 offset0:99 offset1:107
	v_lshl_add_u64 v[82:83], v[8:9], 1, v[6:7]
	s_waitcnt lgkmcnt(0)
	ds_read2_b32 v[90:91], v43 offset0:132 offset1:140
	ds_read2_b32 v[92:93], v43 offset0:165 offset1:173
	v_cvt_pk_bf16_f32 v8, v80, v84
	ds_read2_b32 v[94:95], v43 offset0:198 offset1:206
	ds_read2_b32 v[96:97], v43 offset0:231 offset1:239
	v_cvt_pk_bf16_f32 v9, v86, v88
	s_waitcnt lgkmcnt(0)
	v_cvt_pk_bf16_f32 v10, v90, v92
	v_add3_u32 v98, v42, v12, v79
	v_ashrrev_i32_e32 v99, 31, v98
	v_lshlrev_b64 v[100:101], 11, v[98:99]
	v_cvt_pk_bf16_f32 v11, v94, v96
	v_lshl_add_u64 v[100:101], v[82:83], 0, v[100:101]
	global_store_dwordx4 v[100:101], v[8:11], off
	v_add_u32_e32 v80, 8, v98
	s_nop 0
	v_cvt_pk_bf16_f32 v8, v81, v85
	v_cvt_pk_bf16_f32 v9, v87, v89
	v_cvt_pk_bf16_f32 v10, v91, v93
	v_ashrrev_i32_e32 v81, 31, v80
	v_lshlrev_b64 v[80:81], 11, v[80:81]
	v_cvt_pk_bf16_f32 v11, v95, v97
	ds_read2_b32 v[84:85], v43 offset0:16 offset1:24
	v_lshl_add_u64 v[80:81], v[82:83], 0, v[80:81]
	global_store_dwordx4 v[80:81], v[8:11], off
	ds_read2_b32 v[80:81], v43 offset0:49 offset1:57
	ds_read2_b32 v[86:87], v43 offset0:82 offset1:90
	ds_read2_b32 v[88:89], v43 offset0:115 offset1:123
	s_waitcnt lgkmcnt(0)
	ds_read2_b32 v[90:91], v43 offset0:148 offset1:156
	ds_read2_b32 v[92:93], v43 offset0:181 offset1:189
	v_cvt_pk_bf16_f32 v8, v84, v80
	ds_read2_b32 v[94:95], v43 offset0:214 offset1:222
	ds_read2_b32 v[96:97], v43 offset0:247 offset1:255
	v_cvt_pk_bf16_f32 v9, v86, v88
	s_waitcnt lgkmcnt(0)
	v_cvt_pk_bf16_f32 v10, v90, v92
	v_add_u32_e32 v100, 16, v98
	v_ashrrev_i32_e32 v101, 31, v100
	v_lshlrev_b64 v[100:101], 11, v[100:101]
	v_cvt_pk_bf16_f32 v11, v94, v96
	v_lshl_add_u64 v[100:101], v[82:83], 0, v[100:101]
	global_store_dwordx4 v[100:101], v[8:11], off
	v_add_u32_e32 v80, 24, v98
	s_nop 0
	v_cvt_pk_bf16_f32 v8, v85, v81
	v_cvt_pk_bf16_f32 v9, v87, v89
	v_cvt_pk_bf16_f32 v10, v91, v93
	v_ashrrev_i32_e32 v81, 31, v80
	v_lshlrev_b64 v[80:81], 11, v[80:81]
	v_cvt_pk_bf16_f32 v11, v95, v97
	v_lshl_add_u64 v[80:81], v[82:83], 0, v[80:81]
	global_store_dwordx4 v[80:81], v[8:11], off
	s_waitcnt lgkmcnt(0)
	v_add_u32_e32 v13, s22, v13
	v_cmp_lt_i32_e32 vcc, s31, v13
	s_or_b64 s[46:47], vcc, s[46:47]
	v_add_u32_e32 v12, s23, v12
	s_andn2_b64 exec, exec, s[46:47]
	s_cbranch_execz .LBB0_1409
.LBB0_1377:
	v_ashrrev_i32_e32 v8, 31, v13
	v_lshrrev_b32_e32 v8, 27, v8
	v_add_u32_e32 v8, v13, v8
	v_ashrrev_i32_e32 v8, 5, v8
	v_lshlrev_b32_e32 v9, 10, v8
	v_add_u32_e32 v10, v5, v12
	v_sub_u32_e32 v10, v10, v9
	v_cmp_lt_i32_e32 vcc, s33, v10
	v_lshlrev_b32_e32 v8, 6, v8
	v_ashrrev_i32_e32 v11, 31, v10
	v_lshl_add_u64 v[10:11], v[10:11], 2, s[20:21]
	v_or_b32_e32 v134, v8, v2
	v_ashrrev_i32_e32 v135, 31, v134
	v_lshlrev_b64 v[166:167], 12, v[134:135]
	v_lshl_add_u64 v[166:167], v[10:11], 0, v[166:167]
	s_mov_b32 s100, 0x2000
	s_mov_b32 s101, 0
	v_mov_b64_e32 v[102:103], 0
	v_mov_b64_e32 v[104:105], 0
	v_mov_b64_e32 v[106:107], 0
	v_mov_b64_e32 v[108:109], 0
	v_mov_b64_e32 v[110:111], 0
	v_mov_b64_e32 v[112:113], 0
	v_mov_b64_e32 v[114:115], 0
	v_mov_b64_e32 v[116:117], 0
	v_mov_b64_e32 v[118:119], 0
	v_mov_b64_e32 v[120:121], 0
	v_mov_b64_e32 v[122:123], 0
	v_mov_b64_e32 v[124:125], 0
	v_mov_b64_e32 v[126:127], 0
	v_mov_b64_e32 v[128:129], 0
	v_mov_b64_e32 v[130:131], 0
	v_mov_b64_e32 v[132:133], 0
	s_mov_b64 s[48:49], exec
	s_andn2_b64 exec, exec, vcc
	s_cbranch_execz .Ltr_skip_1377
	global_load_dword v102, v[166:167], off
	v_lshl_add_u64 v[166:167], v[166:167], 0, s[100:101]
	global_load_dword v103, v[166:167], off
	v_lshl_add_u64 v[166:167], v[166:167], 0, s[100:101]
	global_load_dword v104, v[166:167], off
	v_lshl_add_u64 v[166:167], v[166:167], 0, s[100:101]
	global_load_dword v105, v[166:167], off
	v_lshl_add_u64 v[166:167], v[166:167], 0, s[100:101]
	global_load_dword v106, v[166:167], off
	v_lshl_add_u64 v[166:167], v[166:167], 0, s[100:101]
	global_load_dword v107, v[166:167], off
	v_lshl_add_u64 v[166:167], v[166:167], 0, s[100:101]
	global_load_dword v108, v[166:167], off
	v_lshl_add_u64 v[166:167], v[166:167], 0, s[100:101]
	global_load_dword v109, v[166:167], off
	v_lshl_add_u64 v[166:167], v[166:167], 0, s[100:101]
	global_load_dword v110, v[166:167], off
	v_lshl_add_u64 v[166:167], v[166:167], 0, s[100:101]
	global_load_dword v111, v[166:167], off
	v_lshl_add_u64 v[166:167], v[166:167], 0, s[100:101]
	global_load_dword v112, v[166:167], off
	v_lshl_add_u64 v[166:167], v[166:167], 0, s[100:101]
	global_load_dword v113, v[166:167], off
	v_lshl_add_u64 v[166:167], v[166:167], 0, s[100:101]
	global_load_dword v114, v[166:167], off
	v_lshl_add_u64 v[166:167], v[166:167], 0, s[100:101]
	global_load_dword v115, v[166:167], off
	v_lshl_add_u64 v[166:167], v[166:167], 0, s[100:101]
	global_load_dword v116, v[166:167], off
	v_lshl_add_u64 v[166:167], v[166:167], 0, s[100:101]
	global_load_dword v117, v[166:167], off
	v_lshl_add_u64 v[166:167], v[166:167], 0, s[100:101]
	global_load_dword v118, v[166:167], off
	v_lshl_add_u64 v[166:167], v[166:167], 0, s[100:101]
	global_load_dword v119, v[166:167], off
	v_lshl_add_u64 v[166:167], v[166:167], 0, s[100:101]
	global_load_dword v120, v[166:167], off
	v_lshl_add_u64 v[166:167], v[166:167], 0, s[100:101]
	global_load_dword v121, v[166:167], off
	v_lshl_add_u64 v[166:167], v[166:167], 0, s[100:101]
	global_load_dword v122, v[166:167], off
	v_lshl_add_u64 v[166:167], v[166:167], 0, s[100:101]
	global_load_dword v123, v[166:167], off
	v_lshl_add_u64 v[166:167], v[166:167], 0, s[100:101]
	global_load_dword v124, v[166:167], off
	v_lshl_add_u64 v[166:167], v[166:167], 0, s[100:101]
	global_load_dword v125, v[166:167], off
	v_lshl_add_u64 v[166:167], v[166:167], 0, s[100:101]
	global_load_dword v126, v[166:167], off
	v_lshl_add_u64 v[166:167], v[166:167], 0, s[100:101]
	global_load_dword v127, v[166:167], off
	v_lshl_add_u64 v[166:167], v[166:167], 0, s[100:101]
	global_load_dword v128, v[166:167], off
	v_lshl_add_u64 v[166:167], v[166:167], 0, s[100:101]
	global_load_dword v129, v[166:167], off
	v_lshl_add_u64 v[166:167], v[166:167], 0, s[100:101]
	global_load_dword v130, v[166:167], off
	v_lshl_add_u64 v[166:167], v[166:167], 0, s[100:101]
	global_load_dword v131, v[166:167], off
	v_lshl_add_u64 v[166:167], v[166:167], 0, s[100:101]
	global_load_dword v132, v[166:167], off
	v_lshl_add_u64 v[166:167], v[166:167], 0, s[100:101]
	global_load_dword v133, v[166:167], off
.Ltr_skip_1377:
	s_mov_b64 exec, s[48:49]
	s_waitcnt vmcnt(0)
	v_add_u32_e32 v166, v16, v17
	ds_write_b32 v166, v102 offset:0
	ds_write_b32 v166, v103 offset:264
	ds_write_b32 v166, v104 offset:528
	ds_write_b32 v166, v105 offset:792
	ds_write_b32 v166, v106 offset:1056
	ds_write_b32 v166, v107 offset:1320
	ds_write_b32 v166, v108 offset:1584
	ds_write_b32 v166, v109 offset:1848
	ds_write_b32 v166, v110 offset:2112
	ds_write_b32 v166, v111 offset:2376
	ds_write_b32 v166, v112 offset:2640
	ds_write_b32 v166, v113 offset:2904
	ds_write_b32 v166, v114 offset:3168
	ds_write_b32 v166, v115 offset:3432
	ds_write_b32 v166, v116 offset:3696
	ds_write_b32 v166, v117 offset:3960
	ds_write_b32 v166, v118 offset:4224
	ds_write_b32 v166, v119 offset:4488
	ds_write_b32 v166, v120 offset:4752
	ds_write_b32 v166, v121 offset:5016
	ds_write_b32 v166, v122 offset:5280
	ds_write_b32 v166, v123 offset:5544
	ds_write_b32 v166, v124 offset:5808
	ds_write_b32 v166, v125 offset:6072
	ds_write_b32 v166, v126 offset:6336
	ds_write_b32 v166, v127 offset:6600
	ds_write_b32 v166, v128 offset:6864
	ds_write_b32 v166, v129 offset:7128
	ds_write_b32 v166, v130 offset:7392
	ds_write_b32 v166, v131 offset:7656
	ds_write_b32 v166, v132 offset:7920
	ds_write_b32 v166, v133 offset:8184
	s_branch .Ltr_cont_1377
.LBB0_1409:
	s_or_b64 exec, exec, s[2:3]
	s_mov_b64 s[20:21], 0
	v_add_u32_e32 v170, 0x500, v28
	v_cmp_le_i32_e32 vcc, s22, v170
	v_subrev_u32_e32 v174, s22, v170
	s_nop 0
	v_cndmask_b32_e32 v170, v170, v174, vcc
	v_cmp_gt_i32_e32 vcc, 0x200, v170
	s_and_saveexec_b64 s[2:3], vcc
	s_cbranch_execz .LBB0_1444
	v_readlane_b32 s52, v252, 16
	v_readlane_b32 s58, v252, 22
	v_readlane_b32 s59, v252, 23
	s_add_u32 s23, s58, s20
	s_addc_u32 s46, s59, s21
	s_lshl_b64 s[20:21], s[50:51], 2
	s_add_u32 s20, s23, s20
	s_addc_u32 s21, s46, s21
	v_lshl_add_u64 v[6:7], s[0:1], 0, v[168:169]
	s_mov_b64 s[46:47], 0xb00000
	v_lshl_add_u64 v[6:7], v[6:7], 0, s[46:47]
	v_lshlrev_b32_e32 v12, 5, v170
	s_lshl_b32 s23, s22, 5
	s_mov_b64 s[46:47], 0
	v_mov_b32_e32 v13, v170
	v_readlane_b32 s53, v252, 17
	v_readlane_b32 s54, v252, 18
	v_readlane_b32 s55, v252, 19
	v_readlane_b32 s56, v252, 20
	v_readlane_b32 s57, v252, 21
	v_readlane_b32 s60, v252, 24
	v_readlane_b32 s61, v252, 25
	v_readlane_b32 s62, v252, 26
	v_readlane_b32 s63, v252, 27
	v_readlane_b32 s64, v252, 28
	v_readlane_b32 s65, v252, 29
	v_readlane_b32 s66, v252, 30
	v_readlane_b32 s67, v252, 31
	s_branch .LBB0_1412

.LBB0_1444:
	s_or_b64 exec, exec, s[2:3]
	s_mov_b64 s[20:21], 0
	v_add_u32_e32 v170, 0x300, v28
	v_cmp_le_i32_e32 vcc, s22, v170
	v_subrev_u32_e32 v174, s22, v170
	s_nop 0
	v_cndmask_b32_e32 v170, v170, v174, vcc
	v_cmp_gt_i32_e32 vcc, 0x200, v170
	s_and_saveexec_b64 s[2:3], vcc
	s_cbranch_execz .LBB0_1479
	v_readlane_b32 s52, v252, 16
	v_readlane_b32 s60, v252, 24
	v_readlane_b32 s61, v252, 25
	s_add_u32 s23, s60, s20
	s_addc_u32 s46, s61, s21
	s_lshl_b64 s[20:21], s[50:51], 2
	s_add_u32 s20, s23, s20
	s_addc_u32 s21, s46, s21
	v_lshl_add_u64 v[6:7], s[0:1], 0, v[168:169]
	s_mov_b64 s[46:47], 0xd00000
	v_lshl_add_u64 v[6:7], v[6:7], 0, s[46:47]
	v_lshlrev_b32_e32 v12, 5, v170
	s_lshl_b32 s23, s22, 5
	s_mov_b64 s[46:47], 0
	v_mov_b32_e32 v13, v170
	v_readlane_b32 s53, v252, 17
	v_readlane_b32 s54, v252, 18
	v_readlane_b32 s55, v252, 19
	v_readlane_b32 s56, v252, 20
	v_readlane_b32 s57, v252, 21
	v_readlane_b32 s58, v252, 22
	v_readlane_b32 s59, v252, 23
	v_readlane_b32 s62, v252, 26
	v_readlane_b32 s63, v252, 27
	v_readlane_b32 s64, v252, 28
	v_readlane_b32 s65, v252, 29
	v_readlane_b32 s66, v252, 30
	v_readlane_b32 s67, v252, 31
	s_branch .LBB0_1447

.Ltr_cont_1483:
	s_waitcnt lgkmcnt(0)
	ds_read2_b32 v[82:83], v43 offset1:8
	ds_read2_b32 v[86:87], v43 offset0:33 offset1:41
	ds_read2_b32 v[88:89], v43 offset0:66 offset1:74
	v_ashrrev_i32_e32 v9, 31, v8
	ds_read2_b32 v[90:91], v43 offset0:99 offset1:107
	v_lshl_add_u64 v[84:85], v[8:9], 1, v[6:7]
	s_waitcnt lgkmcnt(0)
	ds_read2_b32 v[92:93], v43 offset0:132 offset1:140
	ds_read2_b32 v[94:95], v43 offset0:165 offset1:173
	v_cvt_pk_bf16_f32 v8, v82, v86
	ds_read2_b32 v[96:97], v43 offset0:198 offset1:206
	ds_read2_b32 v[98:99], v43 offset0:231 offset1:239
	v_cvt_pk_bf16_f32 v9, v88, v90
	s_waitcnt lgkmcnt(0)
	v_cvt_pk_bf16_f32 v10, v92, v94
	v_add3_u32 v12, v42, v79, v12
	v_cvt_pk_bf16_f32 v11, v96, v98
	v_ashrrev_i32_e32 v13, 31, v12
	v_lshlrev_b64 v[100:101], 11, v[12:13]
	v_lshl_add_u64 v[100:101], v[84:85], 0, v[100:101]
	global_store_dwordx4 v[100:101], v[8:11], off
	v_add_u32_e32 v82, 8, v12
	s_nop 0
	v_cvt_pk_bf16_f32 v8, v83, v87
	v_cvt_pk_bf16_f32 v9, v89, v91
	v_cvt_pk_bf16_f32 v10, v93, v95
	v_ashrrev_i32_e32 v83, 31, v82
	v_lshlrev_b64 v[82:83], 11, v[82:83]
	v_cvt_pk_bf16_f32 v11, v97, v99
	ds_read2_b32 v[86:87], v43 offset0:16 offset1:24
	v_lshl_add_u64 v[82:83], v[84:85], 0, v[82:83]
	global_store_dwordx4 v[82:83], v[8:11], off
	ds_read2_b32 v[82:83], v43 offset0:49 offset1:57
	ds_read2_b32 v[88:89], v43 offset0:82 offset1:90
	ds_read2_b32 v[90:91], v43 offset0:115 offset1:123
	s_waitcnt lgkmcnt(0)
	ds_read2_b32 v[92:93], v43 offset0:148 offset1:156
	ds_read2_b32 v[94:95], v43 offset0:181 offset1:189
	v_cvt_pk_bf16_f32 v8, v86, v82
	ds_read2_b32 v[96:97], v43 offset0:214 offset1:222
	ds_read2_b32 v[98:99], v43 offset0:247 offset1:255
	v_cvt_pk_bf16_f32 v9, v88, v90
	s_waitcnt lgkmcnt(0)
	v_cvt_pk_bf16_f32 v10, v92, v94
	v_add_u32_e32 v100, 16, v12
	v_ashrrev_i32_e32 v101, 31, v100
	v_lshlrev_b64 v[100:101], 11, v[100:101]
	v_cvt_pk_bf16_f32 v11, v96, v98
	v_lshl_add_u64 v[100:101], v[84:85], 0, v[100:101]
	global_store_dwordx4 v[100:101], v[8:11], off
	s_nop 1
	v_cvt_pk_bf16_f32 v8, v87, v83
	v_cvt_pk_bf16_f32 v9, v89, v91
	v_cvt_pk_bf16_f32 v10, v93, v95
	v_add_u32_e32 v12, 24, v12
	v_cvt_pk_bf16_f32 v11, v97, v99
	v_ashrrev_i32_e32 v13, 31, v12
	v_lshlrev_b64 v[12:13], 11, v[12:13]
	v_lshl_add_u64 v[12:13], v[84:85], 0, v[12:13]
	global_store_dwordx4 v[12:13], v[8:11], off
	s_waitcnt lgkmcnt(0)
	v_add_u32_e32 v80, s22, v80
	s_movk_i32 s46, 0x7ff
	v_cmp_lt_i32_e32 vcc, s46, v80
	s_or_b64 s[52:53], vcc, s[52:53]
	v_add_u32_e32 v79, s23, v79
	s_andn2_b64 exec, exec, s[52:53]
	s_cbranch_execz .LBB0_1610
.LBB0_1483:
	v_ashrrev_i32_e32 v8, 31, v80
	v_lshrrev_b32_e32 v8, 25, v8
	v_add_u32_e32 v8, v80, v8
	v_ashrrev_i32_e32 v8, 7, v8
	v_lshlrev_b32_e32 v81, 12, v8
	v_add_u32_e32 v9, v5, v79
	v_sub_u32_e32 v10, v9, v81
	s_movk_i32 s46, 0xfff
	v_cmp_lt_i32_e64 s[48:49], s46, v10
	v_lshlrev_b32_e32 v8, 6, v8
	v_ashrrev_i32_e32 v11, 31, v10
	v_lshl_add_u64 v[10:11], v[10:11], 2, s[50:51]
	v_sub_u32_e32 v12, 0, v81
	v_or_b32_e32 v134, v8, v2
	v_ashrrev_i32_e32 v135, 31, v134
	v_lshlrev_b64 v[166:167], 14, v[134:135]
	v_lshl_add_u64 v[166:167], v[10:11], 0, v[166:167]
	s_mov_b32 s100, 0x8000
	s_mov_b32 s101, 0
	v_mov_b64_e32 v[102:103], 0
	v_mov_b64_e32 v[104:105], 0
	v_mov_b64_e32 v[106:107], 0
	v_mov_b64_e32 v[108:109], 0
	v_mov_b64_e32 v[110:111], 0
	v_mov_b64_e32 v[112:113], 0
	v_mov_b64_e32 v[114:115], 0
	v_mov_b64_e32 v[116:117], 0
	v_mov_b64_e32 v[118:119], 0
	v_mov_b64_e32 v[120:121], 0
	v_mov_b64_e32 v[122:123], 0
	v_mov_b64_e32 v[124:125], 0
	v_mov_b64_e32 v[126:127], 0
	v_mov_b64_e32 v[128:129], 0
	v_mov_b64_e32 v[130:131], 0
	v_mov_b64_e32 v[132:133], 0
	s_mov_b64 s[54:55], exec
	s_andn2_b64 exec, exec, s[48:49]
	s_cbranch_execz .Ltr_skip_1483
	global_load_dword v102, v[166:167], off
	v_lshl_add_u64 v[166:167], v[166:167], 0, s[100:101]
	global_load_dword v103, v[166:167], off
	v_lshl_add_u64 v[166:167], v[166:167], 0, s[100:101]
	global_load_dword v104, v[166:167], off
	v_lshl_add_u64 v[166:167], v[166:167], 0, s[100:101]
	global_load_dword v105, v[166:167], off
	v_lshl_add_u64 v[166:167], v[166:167], 0, s[100:101]
	global_load_dword v106, v[166:167], off
	v_lshl_add_u64 v[166:167], v[166:167], 0, s[100:101]
	global_load_dword v107, v[166:167], off
	v_lshl_add_u64 v[166:167], v[166:167], 0, s[100:101]
	global_load_dword v108, v[166:167], off
	v_lshl_add_u64 v[166:167], v[166:167], 0, s[100:101]
	global_load_dword v109, v[166:167], off
	v_lshl_add_u64 v[166:167], v[166:167], 0, s[100:101]
	global_load_dword v110, v[166:167], off
	v_lshl_add_u64 v[166:167], v[166:167], 0, s[100:101]
	global_load_dword v111, v[166:167], off
	v_lshl_add_u64 v[166:167], v[166:167], 0, s[100:101]
	global_load_dword v112, v[166:167], off
	v_lshl_add_u64 v[166:167], v[166:167], 0, s[100:101]
	global_load_dword v113, v[166:167], off
	v_lshl_add_u64 v[166:167], v[166:167], 0, s[100:101]
	global_load_dword v114, v[166:167], off
	v_lshl_add_u64 v[166:167], v[166:167], 0, s[100:101]
	global_load_dword v115, v[166:167], off
	v_lshl_add_u64 v[166:167], v[166:167], 0, s[100:101]
	global_load_dword v116, v[166:167], off
	v_lshl_add_u64 v[166:167], v[166:167], 0, s[100:101]
	global_load_dword v117, v[166:167], off
	v_lshl_add_u64 v[166:167], v[166:167], 0, s[100:101]
	global_load_dword v118, v[166:167], off
	v_lshl_add_u64 v[166:167], v[166:167], 0, s[100:101]
	global_load_dword v119, v[166:167], off
	v_lshl_add_u64 v[166:167], v[166:167], 0, s[100:101]
	global_load_dword v120, v[166:167], off
	v_lshl_add_u64 v[166:167], v[166:167], 0, s[100:101]
	global_load_dword v121, v[166:167], off
	v_lshl_add_u64 v[166:167], v[166:167], 0, s[100:101]
	global_load_dword v122, v[166:167], off
	v_lshl_add_u64 v[166:167], v[166:167], 0, s[100:101]
	global_load_dword v123, v[166:167], off
	v_lshl_add_u64 v[166:167], v[166:167], 0, s[100:101]
	global_load_dword v124, v[166:167], off
	v_lshl_add_u64 v[166:167], v[166:167], 0, s[100:101]
	global_load_dword v125, v[166:167], off
	v_lshl_add_u64 v[166:167], v[166:167], 0, s[100:101]
	global_load_dword v126, v[166:167], off
	v_lshl_add_u64 v[166:167], v[166:167], 0, s[100:101]
	global_load_dword v127, v[166:167], off
	v_lshl_add_u64 v[166:167], v[166:167], 0, s[100:101]
	global_load_dword v128, v[166:167], off
	v_lshl_add_u64 v[166:167], v[166:167], 0, s[100:101]
	global_load_dword v129, v[166:167], off
	v_lshl_add_u64 v[166:167], v[166:167], 0, s[100:101]
	global_load_dword v130, v[166:167], off
	v_lshl_add_u64 v[166:167], v[166:167], 0, s[100:101]
	global_load_dword v131, v[166:167], off
	v_lshl_add_u64 v[166:167], v[166:167], 0, s[100:101]
	global_load_dword v132, v[166:167], off
	v_lshl_add_u64 v[166:167], v[166:167], 0, s[100:101]
	global_load_dword v133, v[166:167], off
.Ltr_skip_1483:
	s_mov_b64 exec, s[54:55]
	v_readlane_b32 s46, v252, 32
	v_readlane_b32 s47, v252, 33
	s_and_b64 vcc, exec, s[46:47]
	s_cbranch_vccz .Ltr_nors_1483
	v_ashrrev_i32_e32 v135, 31, v134
	v_lshl_add_u64 v[166:167], v[134:135], 2, s[26:27]
	global_load_dword v134, v[166:167], off offset:0
	global_load_dword v135, v[166:167], off offset:8
	global_load_dword v136, v[166:167], off offset:16
	global_load_dword v137, v[166:167], off offset:24
	global_load_dword v138, v[166:167], off offset:32
	global_load_dword v139, v[166:167], off offset:40
	global_load_dword v140, v[166:167], off offset:48
	global_load_dword v141, v[166:167], off offset:56
	global_load_dword v142, v[166:167], off offset:64
	global_load_dword v143, v[166:167], off offset:72
	global_load_dword v144, v[166:167], off offset:80
	global_load_dword v145, v[166:167], off offset:88
	global_load_dword v146, v[166:167], off offset:96
	global_load_dword v147, v[166:167], off offset:104
	global_load_dword v148, v[166:167], off offset:112
	global_load_dword v149, v[166:167], off offset:120
	global_load_dword v150, v[166:167], off offset:128
	global_load_dword v151, v[166:167], off offset:136
	global_load_dword v152, v[166:167], off offset:144
	global_load_dword v153, v[166:167], off offset:152
	global_load_dword v154, v[166:167], off offset:160
	global_load_dword v155, v[166:167], off offset:168
	global_load_dword v156, v[166:167], off offset:176
	global_load_dword v157, v[166:167], off offset:184
	global_load_dword v158, v[166:167], off offset:192
	global_load_dword v159, v[166:167], off offset:200
	global_load_dword v160, v[166:167], off offset:208
	global_load_dword v161, v[166:167], off offset:216
	global_load_dword v162, v[166:167], off offset:224
	global_load_dword v163, v[166:167], off offset:232
	global_load_dword v164, v[166:167], off offset:240
	global_load_dword v165, v[166:167], off offset:248
	s_waitcnt vmcnt(0)
	v_mul_f32_e32 v102, v102, v134
	v_mul_f32_e32 v103, v103, v135
	v_mul_f32_e32 v104, v104, v136
	v_mul_f32_e32 v105, v105, v137
	v_mul_f32_e32 v106, v106, v138
	v_mul_f32_e32 v107, v107, v139
	v_mul_f32_e32 v108, v108, v140
	v_mul_f32_e32 v109, v109, v141
	v_mul_f32_e32 v110, v110, v142
	v_mul_f32_e32 v111, v111, v143
	v_mul_f32_e32 v112, v112, v144
	v_mul_f32_e32 v113, v113, v145
	v_mul_f32_e32 v114, v114, v146
	v_mul_f32_e32 v115, v115, v147
	v_mul_f32_e32 v116, v116, v148
	v_mul_f32_e32 v117, v117, v149
	v_mul_f32_e32 v118, v118, v150
	v_mul_f32_e32 v119, v119, v151
	v_mul_f32_e32 v120, v120, v152
	v_mul_f32_e32 v121, v121, v153
	v_mul_f32_e32 v122, v122, v154
	v_mul_f32_e32 v123, v123, v155
	v_mul_f32_e32 v124, v124, v156
	v_mul_f32_e32 v125, v125, v157
	v_mul_f32_e32 v126, v126, v158
	v_mul_f32_e32 v127, v127, v159
	v_mul_f32_e32 v128, v128, v160
	v_mul_f32_e32 v129, v129, v161
	v_mul_f32_e32 v130, v130, v162
	v_mul_f32_e32 v131, v131, v163
	v_mul_f32_e32 v132, v132, v164
	v_mul_f32_e32 v133, v133, v165
	s_branch .Ltr_wr_1483

.Ltr_cont_1613:
	s_waitcnt lgkmcnt(0)
	ds_read2_b32 v[80:81], v43 offset1:8
	ds_read2_b32 v[84:85], v43 offset0:33 offset1:41
	ds_read2_b32 v[86:87], v43 offset0:66 offset1:74
	v_sub_u32_e32 v79, 0, v9
	v_ashrrev_i32_e32 v9, 31, v8
	ds_read2_b32 v[88:89], v43 offset0:99 offset1:107
	v_lshl_add_u64 v[82:83], v[8:9], 1, v[6:7]
	s_waitcnt lgkmcnt(0)
	ds_read2_b32 v[90:91], v43 offset0:132 offset1:140
	ds_read2_b32 v[92:93], v43 offset0:165 offset1:173
	v_cvt_pk_bf16_f32 v8, v80, v84
	ds_read2_b32 v[94:95], v43 offset0:198 offset1:206
	ds_read2_b32 v[96:97], v43 offset0:231 offset1:239
	v_cvt_pk_bf16_f32 v9, v86, v88
	s_waitcnt lgkmcnt(0)
	v_cvt_pk_bf16_f32 v10, v90, v92
	v_add3_u32 v98, v42, v12, v79
	v_ashrrev_i32_e32 v99, 31, v98
	v_lshlrev_b64 v[100:101], 13, v[98:99]
	v_cvt_pk_bf16_f32 v11, v94, v96
	v_lshl_add_u64 v[100:101], v[82:83], 0, v[100:101]
	global_store_dwordx4 v[100:101], v[8:11], off
	v_add_u32_e32 v80, 8, v98
	s_nop 0
	v_cvt_pk_bf16_f32 v8, v81, v85
	v_cvt_pk_bf16_f32 v9, v87, v89
	v_cvt_pk_bf16_f32 v10, v91, v93
	v_ashrrev_i32_e32 v81, 31, v80
	v_lshlrev_b64 v[80:81], 13, v[80:81]
	v_cvt_pk_bf16_f32 v11, v95, v97
	ds_read2_b32 v[84:85], v43 offset0:16 offset1:24
	v_lshl_add_u64 v[80:81], v[82:83], 0, v[80:81]
	global_store_dwordx4 v[80:81], v[8:11], off
	ds_read2_b32 v[80:81], v43 offset0:49 offset1:57
	ds_read2_b32 v[86:87], v43 offset0:82 offset1:90
	ds_read2_b32 v[88:89], v43 offset0:115 offset1:123
	s_waitcnt lgkmcnt(0)
	ds_read2_b32 v[90:91], v43 offset0:148 offset1:156
	ds_read2_b32 v[92:93], v43 offset0:181 offset1:189
	v_cvt_pk_bf16_f32 v8, v84, v80
	ds_read2_b32 v[94:95], v43 offset0:214 offset1:222
	ds_read2_b32 v[96:97], v43 offset0:247 offset1:255
	v_cvt_pk_bf16_f32 v9, v86, v88
	s_waitcnt lgkmcnt(0)
	v_cvt_pk_bf16_f32 v10, v90, v92
	v_add_u32_e32 v100, 16, v98
	v_ashrrev_i32_e32 v101, 31, v100
	v_lshlrev_b64 v[100:101], 13, v[100:101]
	v_cvt_pk_bf16_f32 v11, v94, v96
	v_lshl_add_u64 v[100:101], v[82:83], 0, v[100:101]
	global_store_dwordx4 v[100:101], v[8:11], off
	v_add_u32_e32 v80, 24, v98
	s_nop 0
	v_cvt_pk_bf16_f32 v8, v85, v81
	v_cvt_pk_bf16_f32 v9, v87, v89
	v_cvt_pk_bf16_f32 v10, v91, v93
	v_ashrrev_i32_e32 v81, 31, v80
	v_lshlrev_b64 v[80:81], 13, v[80:81]
	v_cvt_pk_bf16_f32 v11, v95, v97
	v_lshl_add_u64 v[80:81], v[82:83], 0, v[80:81]
	global_store_dwordx4 v[80:81], v[8:11], off
	s_waitcnt lgkmcnt(0)
	v_add_u32_e32 v13, s22, v13
	s_movk_i32 s46, 0x7ff
	v_cmp_lt_i32_e32 vcc, s46, v13
	s_or_b64 s[26:27], vcc, s[26:27]
	v_add_u32_e32 v12, s23, v12
	s_andn2_b64 exec, exec, s[26:27]
	s_cbranch_execz .LBB0_1645
.LBB0_1613:
	v_ashrrev_i32_e32 v8, 31, v13
	v_lshrrev_b32_e32 v8, 27, v8
	v_add_u32_e32 v8, v13, v8
	v_ashrrev_i32_e32 v8, 5, v8
	v_lshlrev_b32_e32 v9, 10, v8
	v_add_u32_e32 v10, v5, v12
	v_sub_u32_e32 v10, v10, v9
	v_cmp_lt_i32_e32 vcc, s33, v10
	v_lshlrev_b32_e32 v8, 6, v8
	v_ashrrev_i32_e32 v11, 31, v10
	v_lshl_add_u64 v[10:11], v[10:11], 2, s[2:3]
	v_or_b32_e32 v134, v8, v2
	v_ashrrev_i32_e32 v135, 31, v134
	v_lshlrev_b64 v[166:167], 12, v[134:135]
	v_lshl_add_u64 v[166:167], v[10:11], 0, v[166:167]
	s_mov_b32 s100, 0x2000
	s_mov_b32 s101, 0
	v_mov_b64_e32 v[102:103], 0
	v_mov_b64_e32 v[104:105], 0
	v_mov_b64_e32 v[106:107], 0
	v_mov_b64_e32 v[108:109], 0
	v_mov_b64_e32 v[110:111], 0
	v_mov_b64_e32 v[112:113], 0
	v_mov_b64_e32 v[114:115], 0
	v_mov_b64_e32 v[116:117], 0
	v_mov_b64_e32 v[118:119], 0
	v_mov_b64_e32 v[120:121], 0
	v_mov_b64_e32 v[122:123], 0
	v_mov_b64_e32 v[124:125], 0
	v_mov_b64_e32 v[126:127], 0
	v_mov_b64_e32 v[128:129], 0
	v_mov_b64_e32 v[130:131], 0
	v_mov_b64_e32 v[132:133], 0
	s_mov_b64 s[46:47], exec
	s_andn2_b64 exec, exec, vcc
	s_cbranch_execz .Ltr_skip_1613
	global_load_dword v102, v[166:167], off
	v_lshl_add_u64 v[166:167], v[166:167], 0, s[100:101]
	global_load_dword v103, v[166:167], off
	v_lshl_add_u64 v[166:167], v[166:167], 0, s[100:101]
	global_load_dword v104, v[166:167], off
	v_lshl_add_u64 v[166:167], v[166:167], 0, s[100:101]
	global_load_dword v105, v[166:167], off
	v_lshl_add_u64 v[166:167], v[166:167], 0, s[100:101]
	global_load_dword v106, v[166:167], off
	v_lshl_add_u64 v[166:167], v[166:167], 0, s[100:101]
	global_load_dword v107, v[166:167], off
	v_lshl_add_u64 v[166:167], v[166:167], 0, s[100:101]
	global_load_dword v108, v[166:167], off
	v_lshl_add_u64 v[166:167], v[166:167], 0, s[100:101]
	global_load_dword v109, v[166:167], off
	v_lshl_add_u64 v[166:167], v[166:167], 0, s[100:101]
	global_load_dword v110, v[166:167], off
	v_lshl_add_u64 v[166:167], v[166:167], 0, s[100:101]
	global_load_dword v111, v[166:167], off
	v_lshl_add_u64 v[166:167], v[166:167], 0, s[100:101]
	global_load_dword v112, v[166:167], off
	v_lshl_add_u64 v[166:167], v[166:167], 0, s[100:101]
	global_load_dword v113, v[166:167], off
	v_lshl_add_u64 v[166:167], v[166:167], 0, s[100:101]
	global_load_dword v114, v[166:167], off
	v_lshl_add_u64 v[166:167], v[166:167], 0, s[100:101]
	global_load_dword v115, v[166:167], off
	v_lshl_add_u64 v[166:167], v[166:167], 0, s[100:101]
	global_load_dword v116, v[166:167], off
	v_lshl_add_u64 v[166:167], v[166:167], 0, s[100:101]
	global_load_dword v117, v[166:167], off
	v_lshl_add_u64 v[166:167], v[166:167], 0, s[100:101]
	global_load_dword v118, v[166:167], off
	v_lshl_add_u64 v[166:167], v[166:167], 0, s[100:101]
	global_load_dword v119, v[166:167], off
	v_lshl_add_u64 v[166:167], v[166:167], 0, s[100:101]
	global_load_dword v120, v[166:167], off
	v_lshl_add_u64 v[166:167], v[166:167], 0, s[100:101]
	global_load_dword v121, v[166:167], off
	v_lshl_add_u64 v[166:167], v[166:167], 0, s[100:101]
	global_load_dword v122, v[166:167], off
	v_lshl_add_u64 v[166:167], v[166:167], 0, s[100:101]
	global_load_dword v123, v[166:167], off
	v_lshl_add_u64 v[166:167], v[166:167], 0, s[100:101]
	global_load_dword v124, v[166:167], off
	v_lshl_add_u64 v[166:167], v[166:167], 0, s[100:101]
	global_load_dword v125, v[166:167], off
	v_lshl_add_u64 v[166:167], v[166:167], 0, s[100:101]
	global_load_dword v126, v[166:167], off
	v_lshl_add_u64 v[166:167], v[166:167], 0, s[100:101]
	global_load_dword v127, v[166:167], off
	v_lshl_add_u64 v[166:167], v[166:167], 0, s[100:101]
	global_load_dword v128, v[166:167], off
	v_lshl_add_u64 v[166:167], v[166:167], 0, s[100:101]
	global_load_dword v129, v[166:167], off
	v_lshl_add_u64 v[166:167], v[166:167], 0, s[100:101]
	global_load_dword v130, v[166:167], off
	v_lshl_add_u64 v[166:167], v[166:167], 0, s[100:101]
	global_load_dword v131, v[166:167], off
	v_lshl_add_u64 v[166:167], v[166:167], 0, s[100:101]
	global_load_dword v132, v[166:167], off
	v_lshl_add_u64 v[166:167], v[166:167], 0, s[100:101]
	global_load_dword v133, v[166:167], off

.LBB0_1645:
	s_or_b64 exec, exec, s[20:21]
	s_mov_b64 s[20:21], 0
	v_add_u32_e32 v170, 0x100, v28
	v_cmp_le_i32_e32 vcc, s22, v170
	v_subrev_u32_e32 v174, s22, v170
	s_nop 0
	v_cndmask_b32_e32 v170, v170, v174, vcc
	v_cmp_gt_i32_e32 vcc, 0x20, v170
	s_and_saveexec_b64 s[2:3], vcc
	s_cbranch_execz .LBB0_1074
	s_add_u32 s23, s88, s20
	s_addc_u32 s26, s89, s21
	s_lshl_b64 s[20:21], s[34:35], 18
	s_add_u32 s20, s23, s20
	v_lshl_add_u64 v[6:7], s[0:1], 0, v[168:169]
	s_mov_b64 s[0:1], 0x1f00000
	s_addc_u32 s21, s26, s21
	v_lshl_add_u64 v[6:7], v[6:7], 0, s[0:1]
	s_lshl_b32 s23, s22, 5
	s_mov_b64 s[0:1], 0
	v_mov_b32_e32 v12, v170
	v_lshlrev_b32_e32 v78, 5, v170
	s_branch .LBB0_1648
.Ltr_cont_1648:
	s_waitcnt lgkmcnt(0)
	ds_read2_b32 v[80:81], v43 offset1:8
	ds_read2_b32 v[84:85], v43 offset0:33 offset1:41
	ds_read2_b32 v[86:87], v43 offset0:66 offset1:74
	v_sub_u32_e32 v13, 0, v9
	v_ashrrev_i32_e32 v9, 31, v8
	ds_read2_b32 v[88:89], v43 offset0:99 offset1:107
	v_lshl_add_u64 v[82:83], v[8:9], 1, v[6:7]
	s_waitcnt lgkmcnt(0)
	ds_read2_b32 v[90:91], v43 offset0:132 offset1:140
	ds_read2_b32 v[92:93], v43 offset0:165 offset1:173
	v_cvt_pk_bf16_f32 v8, v80, v84
	ds_read2_b32 v[94:95], v43 offset0:198 offset1:206
	ds_read2_b32 v[96:97], v43 offset0:231 offset1:239
	v_cvt_pk_bf16_f32 v9, v86, v88
	s_waitcnt lgkmcnt(0)
	v_cvt_pk_bf16_f32 v10, v90, v92
	v_add3_u32 v98, v42, v78, v13
	v_ashrrev_i32_e32 v99, 31, v98
	v_lshlrev_b64 v[100:101], 9, v[98:99]
	v_cvt_pk_bf16_f32 v11, v94, v96
	v_lshl_add_u64 v[100:101], v[82:83], 0, v[100:101]
	global_store_dwordx4 v[100:101], v[8:11], off
	v_add_u32_e32 v80, 8, v98
	s_nop 0
	v_cvt_pk_bf16_f32 v8, v81, v85
	v_cvt_pk_bf16_f32 v9, v87, v89
	v_cvt_pk_bf16_f32 v10, v91, v93
	v_ashrrev_i32_e32 v81, 31, v80
	v_lshlrev_b64 v[80:81], 9, v[80:81]
	v_cvt_pk_bf16_f32 v11, v95, v97
	ds_read2_b32 v[84:85], v43 offset0:16 offset1:24
	v_lshl_add_u64 v[80:81], v[82:83], 0, v[80:81]
	global_store_dwordx4 v[80:81], v[8:11], off
	ds_read2_b32 v[80:81], v43 offset0:49 offset1:57
	ds_read2_b32 v[86:87], v43 offset0:82 offset1:90
	ds_read2_b32 v[88:89], v43 offset0:115 offset1:123
	s_waitcnt lgkmcnt(0)
	ds_read2_b32 v[90:91], v43 offset0:148 offset1:156
	ds_read2_b32 v[92:93], v43 offset0:181 offset1:189
	v_cvt_pk_bf16_f32 v8, v84, v80
	ds_read2_b32 v[94:95], v43 offset0:214 offset1:222
	ds_read2_b32 v[96:97], v43 offset0:247 offset1:255
	v_cvt_pk_bf16_f32 v9, v86, v88
	s_waitcnt lgkmcnt(0)
	v_cvt_pk_bf16_f32 v10, v90, v92
	v_add_u32_e32 v100, 16, v98
	v_ashrrev_i32_e32 v101, 31, v100
	v_lshlrev_b64 v[100:101], 9, v[100:101]
	v_cvt_pk_bf16_f32 v11, v94, v96
	v_lshl_add_u64 v[100:101], v[82:83], 0, v[100:101]
	global_store_dwordx4 v[100:101], v[8:11], off
	v_add_u32_e32 v80, 24, v98
	s_nop 0
	v_cvt_pk_bf16_f32 v8, v85, v81
	v_cvt_pk_bf16_f32 v9, v87, v89
	v_cvt_pk_bf16_f32 v10, v91, v93
	v_ashrrev_i32_e32 v81, 31, v80
	v_lshlrev_b64 v[80:81], 9, v[80:81]
	v_cvt_pk_bf16_f32 v11, v95, v97
	v_lshl_add_u64 v[80:81], v[82:83], 0, v[80:81]
	global_store_dwordx4 v[80:81], v[8:11], off
	s_waitcnt lgkmcnt(0)
	v_add_u32_e32 v12, s22, v12
	v_cmp_lt_i32_e32 vcc, 31, v12
	s_or_b64 s[0:1], vcc, s[0:1]
	v_add_u32_e32 v78, s23, v78
	s_andn2_b64 exec, exec, s[0:1]
	s_cbranch_execz .LBB0_1074
.LBB0_1648:
	v_ashrrev_i32_e32 v8, 31, v12
	v_lshrrev_b32_e32 v8, 29, v8
	v_add_u32_e32 v8, v12, v8
	v_ashrrev_i32_e32 v8, 3, v8
	v_lshlrev_b32_e32 v9, 8, v8
	v_add_u32_e32 v10, v5, v78
	v_sub_u32_e32 v10, v10, v9
	s_movk_i32 s26, 0xff
	v_cmp_lt_i32_e32 vcc, s26, v10
	v_add_u32_e32 v13, v16, v17
	v_lshlrev_b32_e32 v8, 6, v8
	v_ashrrev_i32_e32 v11, 31, v10
	v_lshl_add_u64 v[10:11], v[10:11], 2, s[20:21]
	v_or_b32_e32 v134, v8, v2
	v_ashrrev_i32_e32 v135, 31, v134
	v_lshlrev_b64 v[166:167], 10, v[134:135]
	v_lshl_add_u64 v[166:167], v[10:11], 0, v[166:167]
	s_mov_b32 s100, 0x800
	s_mov_b32 s101, 0
	v_mov_b64_e32 v[102:103], 0
	v_mov_b64_e32 v[104:105], 0
	v_mov_b64_e32 v[106:107], 0
	v_mov_b64_e32 v[108:109], 0
	v_mov_b64_e32 v[110:111], 0
	v_mov_b64_e32 v[112:113], 0
	v_mov_b64_e32 v[114:115], 0
	v_mov_b64_e32 v[116:117], 0
	v_mov_b64_e32 v[118:119], 0
	v_mov_b64_e32 v[120:121], 0
	v_mov_b64_e32 v[122:123], 0
	v_mov_b64_e32 v[124:125], 0
	v_mov_b64_e32 v[126:127], 0
	v_mov_b64_e32 v[128:129], 0
	v_mov_b64_e32 v[130:131], 0
	v_mov_b64_e32 v[132:133], 0
	s_mov_b64 s[26:27], exec
	s_andn2_b64 exec, exec, vcc
	s_cbranch_execz .Ltr_skip_1648
	global_load_dword v102, v[166:167], off
	v_lshl_add_u64 v[166:167], v[166:167], 0, s[100:101]
	global_load_dword v103, v[166:167], off
	v_lshl_add_u64 v[166:167], v[166:167], 0, s[100:101]
	global_load_dword v104, v[166:167], off
	v_lshl_add_u64 v[166:167], v[166:167], 0, s[100:101]
	global_load_dword v105, v[166:167], off
	v_lshl_add_u64 v[166:167], v[166:167], 0, s[100:101]
	global_load_dword v106, v[166:167], off
	v_lshl_add_u64 v[166:167], v[166:167], 0, s[100:101]
	global_load_dword v107, v[166:167], off
	v_lshl_add_u64 v[166:167], v[166:167], 0, s[100:101]
	global_load_dword v108, v[166:167], off
	v_lshl_add_u64 v[166:167], v[166:167], 0, s[100:101]
	global_load_dword v109, v[166:167], off
	v_lshl_add_u64 v[166:167], v[166:167], 0, s[100:101]
	global_load_dword v110, v[166:167], off
	v_lshl_add_u64 v[166:167], v[166:167], 0, s[100:101]
	global_load_dword v111, v[166:167], off
	v_lshl_add_u64 v[166:167], v[166:167], 0, s[100:101]
	global_load_dword v112, v[166:167], off
	v_lshl_add_u64 v[166:167], v[166:167], 0, s[100:101]
	global_load_dword v113, v[166:167], off
	v_lshl_add_u64 v[166:167], v[166:167], 0, s[100:101]
	global_load_dword v114, v[166:167], off
	v_lshl_add_u64 v[166:167], v[166:167], 0, s[100:101]
	global_load_dword v115, v[166:167], off
	v_lshl_add_u64 v[166:167], v[166:167], 0, s[100:101]
	global_load_dword v116, v[166:167], off
	v_lshl_add_u64 v[166:167], v[166:167], 0, s[100:101]
	global_load_dword v117, v[166:167], off
	v_lshl_add_u64 v[166:167], v[166:167], 0, s[100:101]
	global_load_dword v118, v[166:167], off
	v_lshl_add_u64 v[166:167], v[166:167], 0, s[100:101]
	global_load_dword v119, v[166:167], off
	v_lshl_add_u64 v[166:167], v[166:167], 0, s[100:101]
	global_load_dword v120, v[166:167], off
	v_lshl_add_u64 v[166:167], v[166:167], 0, s[100:101]
	global_load_dword v121, v[166:167], off
	v_lshl_add_u64 v[166:167], v[166:167], 0, s[100:101]
	global_load_dword v122, v[166:167], off
	v_lshl_add_u64 v[166:167], v[166:167], 0, s[100:101]
	global_load_dword v123, v[166:167], off
	v_lshl_add_u64 v[166:167], v[166:167], 0, s[100:101]
	global_load_dword v124, v[166:167], off
	v_lshl_add_u64 v[166:167], v[166:167], 0, s[100:101]
	global_load_dword v125, v[166:167], off
	v_lshl_add_u64 v[166:167], v[166:167], 0, s[100:101]
	global_load_dword v126, v[166:167], off
	v_lshl_add_u64 v[166:167], v[166:167], 0, s[100:101]
	global_load_dword v127, v[166:167], off
	v_lshl_add_u64 v[166:167], v[166:167], 0, s[100:101]
	global_load_dword v128, v[166:167], off
	v_lshl_add_u64 v[166:167], v[166:167], 0, s[100:101]
	global_load_dword v129, v[166:167], off
	v_lshl_add_u64 v[166:167], v[166:167], 0, s[100:101]
	global_load_dword v130, v[166:167], off
	v_lshl_add_u64 v[166:167], v[166:167], 0, s[100:101]
	global_load_dword v131, v[166:167], off
	v_lshl_add_u64 v[166:167], v[166:167], 0, s[100:101]
	global_load_dword v132, v[166:167], off
	v_lshl_add_u64 v[166:167], v[166:167], 0, s[100:101]
	global_load_dword v133, v[166:167], off
.Ltr_skip_1648:
	s_mov_b64 exec, s[26:27]
	s_waitcnt vmcnt(0)
	v_add_u32_e32 v166, v16, v17
	ds_write_b32 v166, v102 offset:0
	ds_write_b32 v166, v103 offset:264
	ds_write_b32 v166, v104 offset:528
	ds_write_b32 v166, v105 offset:792
	ds_write_b32 v166, v106 offset:1056
	ds_write_b32 v166, v107 offset:1320
	ds_write_b32 v166, v108 offset:1584
	ds_write_b32 v166, v109 offset:1848
	ds_write_b32 v166, v110 offset:2112
	ds_write_b32 v166, v111 offset:2376
	ds_write_b32 v166, v112 offset:2640
	ds_write_b32 v166, v113 offset:2904
	ds_write_b32 v166, v114 offset:3168
	ds_write_b32 v166, v115 offset:3432
	ds_write_b32 v166, v116 offset:3696
	ds_write_b32 v166, v117 offset:3960
	ds_write_b32 v166, v118 offset:4224
	ds_write_b32 v166, v119 offset:4488
	ds_write_b32 v166, v120 offset:4752
	ds_write_b32 v166, v121 offset:5016
	ds_write_b32 v166, v122 offset:5280
	ds_write_b32 v166, v123 offset:5544
	ds_write_b32 v166, v124 offset:5808
	ds_write_b32 v166, v125 offset:6072
	ds_write_b32 v166, v126 offset:6336
	ds_write_b32 v166, v127 offset:6600
	ds_write_b32 v166, v128 offset:6864
	ds_write_b32 v166, v129 offset:7128
	ds_write_b32 v166, v130 offset:7392
	ds_write_b32 v166, v131 offset:7656
	ds_write_b32 v166, v132 offset:7920
	ds_write_b32 v166, v133 offset:8184
	s_branch .Ltr_cont_1648

	.amdhsa_kernel _Z3fwd4Args
		.amdhsa_group_segment_fixed_size 0
		.amdhsa_private_segment_fixed_size 0
		.amdhsa_kernarg_size 568
		.amdhsa_user_sgpr_count 2
		.amdhsa_user_sgpr_dispatch_ptr 0
		.amdhsa_user_sgpr_queue_ptr 0
		.amdhsa_user_sgpr_kernarg_segment_ptr 1
		.amdhsa_user_sgpr_dispatch_id 0
		.amdhsa_user_sgpr_kernarg_preload_length 0
		.amdhsa_user_sgpr_kernarg_preload_offset 0
		.amdhsa_user_sgpr_private_segment_size 0
		.amdhsa_uses_dynamic_stack 0
		.amdhsa_enable_private_segment 0
		.amdhsa_system_sgpr_workgroup_id_x 1
		.amdhsa_system_sgpr_workgroup_id_y 0
		.amdhsa_system_sgpr_workgroup_id_z 0
		.amdhsa_system_sgpr_workgroup_info 0
		.amdhsa_system_vgpr_workitem_id 2
		.amdhsa_next_free_vgpr 256
		.amdhsa_next_free_sgpr 102
		.amdhsa_accum_offset 256
		.amdhsa_reserve_vcc 1
		.amdhsa_float_round_mode_32 0
		.amdhsa_float_round_mode_16_64 0
		.amdhsa_float_denorm_mode_32 3
		.amdhsa_float_denorm_mode_16_64 3
		.amdhsa_dx10_clamp 1
		.amdhsa_ieee_mode 1
		.amdhsa_fp16_overflow 0
		.amdhsa_tg_split 0
		.amdhsa_exception_fp_ieee_invalid_op 0
		.amdhsa_exception_fp_denorm_src 0
		.amdhsa_exception_fp_ieee_div_zero 0
		.amdhsa_exception_fp_ieee_overflow 0
		.amdhsa_exception_fp_ieee_underflow 0
		.amdhsa_exception_fp_ieee_inexact 0
		.amdhsa_exception_int_div_zero 0
	.end_amdhsa_kernel

amdhsa.kernels:
  - .agpr_count:     0
    .args:
      - .offset:         0
        .size:           312
        .value_kind:     by_value
      - .offset:         312
        .size:           4
        .value_kind:     hidden_block_count_x
      - .offset:         316
        .size:           4
        .value_kind:     hidden_block_count_y
      - .offset:         320
        .size:           4
        .value_kind:     hidden_block_count_z
      - .offset:         324
        .size:           2
        .value_kind:     hidden_group_size_x
      - .offset:         326
        .size:           2
        .value_kind:     hidden_group_size_y
      - .offset:         328
        .size:           2
        .value_kind:     hidden_group_size_z
      - .offset:         330
        .size:           2
        .value_kind:     hidden_remainder_x
      - .offset:         332
        .size:           2
        .value_kind:     hidden_remainder_y
      - .offset:         334
        .size:           2
        .value_kind:     hidden_remainder_z
      - .offset:         352
        .size:           8
        .value_kind:     hidden_global_offset_x
      - .offset:         360
        .size:           8
        .value_kind:     hidden_global_offset_y
      - .offset:         368
        .size:           8
        .value_kind:     hidden_global_offset_z
      - .offset:         376
        .size:           2
        .value_kind:     hidden_grid_dims
      - .offset:         400
        .size:           8
        .value_kind:     hidden_multigrid_sync_arg
      - .offset:         432
        .size:           4
        .value_kind:     hidden_dynamic_lds_size
    .group_segment_fixed_size: 0
    .kernarg_segment_align: 8
    .kernarg_segment_size: 568
    .language:       OpenCL C
    .language_version:
      - 2
      - 0
    .max_flat_workgroup_size: 512
    .name:           _Z3fwd4Args
    .private_segment_fixed_size: 0
    .sgpr_count:     108
    .sgpr_spill_count: 225
    .symbol:         _Z3fwd4Args.kd
    .uniform_work_group_size: 1
    .uses_dynamic_stack: false
    .vgpr_count:     256
    .vgpr_spill_count: 0
    .wavefront_size: 64
